# lru gates: first eight weight-fragment loads prefetched at the unit's input stage
# speedup vs baseline: 1.0040x; 1.0040x over previous
; __device__ __forceinline__ float bf2f(bf16_t v) { return __uint_as_float(((unsigned)v) << 16); }
; __device__ void lru_local_unit(const Params& p, unsigned char* smem, int unit) {
;     ...
; #pragma unroll 11
;   for (int e = tid; e < 131 * 64; e += HTHR) {
;     const int r = e >> 6, j = e & 63, tt = r - 3;
;     float v = 0.f;
;     if (c * 128 + tt >= 0) v = bf2f(proj[(size_t)(t0 + tt) * LDP + ch0 + j]);
;     ...
;     const bf16_t* waT = (const bf16_t*)(ws + OFF_WAT) + (size_t)hh * 4096;
;     const bf16_t* wxT = (const bf16_t*)(ws + OFF_WXT) + (size_t)hh * 4096;
;     f32x4 aa[2][4], ax[2][4];
; #pragma unroll
;     for (int i = 0; i < 2; ++i)
; #pragma unroll
;       for (int j = 0; j < 4; ++j) { aa[i][j] = (f32x4){0, 0, 0, 0}; ax[i][j] = (f32x4){0, 0, 0, 0}; }
; #pragma unroll
;     for (int ks = 0; ks < 2; ++ks) {
;       bf16x8 af[2];
; #pragma unroll
;       for (int mi = 0; mi < 2; ++mi) {
;         const float* src = R2 + (wid * 32 + mi * 16 + l15) * 64 + ks * 32 + q4 * 8;
;         f32x4 v0 = *(const f32x4*)src, v1 = *(const f32x4*)(src + 4);
;         u32x4 r = {pk2(v0[0], v0[1]), pk2(v0[2], v0[3]), pk2(v1[0], v1[1]), pk2(v1[2], v1[3])};
;         af[mi] = as_frag(r);
;       }
; #pragma unroll
;       for (int ni = 0; ni < 4; ++ni) {
;         const size_t wo = (size_t)(ni * 16 + l15) * 64 + ks * 32 + q4 * 8;
;         bf16x8 ba = as_frag(*(const u32x4*)(waT + wo));
;         bf16x8 bx = as_frag(*(const u32x4*)(wxT + wo));
.LBB0_505:
	s_or_b64 exec, exec, s[66:67]
	v_lshlrev_b32_e32 v68, 13, v16
	v_lshl_add_u64 v[248:249], s[14:15], 0, v[68:69]
	v_lshl_add_u64 v[248:249], v[248:249], 0, v[82:83]
	global_load_dwordx4 v[216:219], v[248:249], off
	global_load_dwordx4 v[224:227], v[248:249], off offset:64
	global_load_dwordx4 v[232:235], v[248:249], off offset:2048
	global_load_dwordx4 v[236:239], v[248:249], off offset:2112
	v_lshl_add_u64 v[248:249], s[10:11], 0, v[68:69]
	v_lshl_add_u64 v[248:249], v[248:249], 0, v[82:83]
	global_load_dwordx4 v[220:223], v[248:249], off
	global_load_dwordx4 v[228:231], v[248:249], off offset:64
	global_load_dwordx4 v[240:243], v[248:249], off offset:2048
	global_load_dwordx4 v[244:247], v[248:249], off offset:2112
	v_add_u32_e32 v6, 0xfffff500, v27
	v_add_u32_e32 v7, 0xa00, v27
	v_add_u32_e32 v9, 0x900, v27
	v_add_u32_e32 v11, 0x800, v27
	v_add_u32_e32 v13, 0x700, v27
	v_add_u32_e32 v15, 0x600, v27
	v_add_u32_e32 v18, 0x500, v27
	v_add_u32_e32 v20, 0x400, v27
	v_add_u32_e32 v22, 0x300, v27
	v_add_u32_e32 v24, 0x200, v27
	v_add_u32_e32 v27, 0x100, v27
	v_lshrrev_b32_e32 v7, 6, v7
	v_lshrrev_b32_e32 v9, 6, v9
	v_lshrrev_b32_e32 v11, 6, v11
	v_lshrrev_b32_e32 v13, 6, v13
	v_lshrrev_b32_e32 v15, 6, v15
	v_lshrrev_b32_e32 v18, 6, v18
	v_lshrrev_b32_e32 v20, 6, v20
	v_lshrrev_b32_e32 v22, 6, v22
	v_lshrrev_b32_e32 v24, 6, v24
	v_lshrrev_b32_e32 v27, 6, v27
	v_add_u32_e32 v7, -3, v7
	v_add_u32_e32 v9, -3, v9
	v_add_u32_e32 v11, -3, v11
	v_add_u32_e32 v13, -3, v13
	v_add_u32_e32 v15, -3, v15
	v_add_u32_e32 v18, -3, v18
	v_add_u32_e32 v20, -3, v20
	v_add_u32_e32 v22, -3, v22
	v_add_u32_e32 v24, -3, v24
	v_add_u32_e32 v27, -3, v27
	v_lshlrev_b32_e32 v128, 6, v16
	v_add_u32_e32 v8, v7, v29
	v_add_u32_e32 v10, v9, v29
	v_add_u32_e32 v12, v11, v29
	v_add_u32_e32 v14, v13, v29
	v_add_u32_e32 v17, v15, v29
	v_add_u32_e32 v19, v18, v29
	v_add_u32_e32 v21, v20, v29
	v_add_u32_e32 v23, v22, v29
	v_add_u32_e32 v25, v24, v29
	v_add_u32_e32 v26, v166, v26
	v_add_u32_e32 v28, v27, v29
	v_add_u32_e32 v29, v5, v29
	s_mov_b32 s3, 0
	s_mov_b64 s[66:67], 0
	s_branch .LBB0_507

; __device__ void lru_local_unit(const Params& p, unsigned char* smem, int unit) {
;     ...
;   {
;     const int j = tid & 63;
;     const float cb = p.lru_conv_b[ch0 + j];
;     const float w0 = p.lru_conv_w[0 * 1024 + ch0 + j], w1 = p.lru_conv_w[1 * 1024 + ch0 + j],
;                 w2 = p.lru_conv_w[2 * 1024 + ch0 + j], w3 = p.lru_conv_w[3 * 1024 + ch0 + j];
; #pragma unroll 8
;     for (int tt = tid >> 6; tt < 128; tt += 4) {
;       R2[tt * 64 + j] = cb + w0 * R1[tt * 64 + j] + w1 * R1[(tt + 1) * 64 + j] + w2 * R1[(tt + 2) * 64 + j] +
;                         w3 * R1[(tt + 3) * 64 + j];
;     }
;   }
.LBB0_530:
	v_lshlrev_b32_e32 v17, 6, v14
	v_lshlrev_b32_e32 v3, 6, v15
	v_lshl_add_u32 v19, v14, 8, v106
	v_lshl_add_u32 v18, v15, 8, v106
	v_or_b32_e32 v27, v17, v138
	v_or_b32_e32 v26, v3, v1
	ds_read2st64_b32 v[20:21], v19 offset0:1 offset1:2
	ds_read_b32 v22, v19 offset:768
	ds_read2st64_b32 v[24:25], v18 offset0:1 offset1:2
	ds_read_b32 v23, v18 offset:768
	v_add_u32_e32 v18, 0x200, v3
	v_add_u32_e32 v19, 0x200, v17
	v_lshl_add_u32 v38, v27, 2, v166
	v_lshl_add_u32 v39, v26, 2, v166
	v_or_b32_e32 v26, v18, v1
	v_or_b32_e32 v27, v19, v138
	v_lshl_add_u32 v40, v19, 2, v106
	v_lshl_add_u32 v41, v18, 2, v106
	ds_read_b32 v18, v38
	ds_read_b32 v19, v39
	v_lshl_add_u32 v54, v27, 2, v166
	v_lshl_add_u32 v55, v26, 2, v166
	s_waitcnt lgkmcnt(5)
	v_mov_b32_e32 v26, v20
	s_waitcnt lgkmcnt(3)
	v_mov_b32_e32 v27, v24
	s_waitcnt lgkmcnt(0)
	v_pk_fma_f32 v[18:19], v[6:7], v[18:19], v[4:5]
	v_mov_b32_e32 v24, v21
	v_pk_fma_f32 v[18:19], v[8:9], v[26:27], v[18:19]
	v_add_u32_e32 v29, 0x400, v17
	v_pk_fma_f32 v[18:19], v[10:11], v[24:25], v[18:19]
	v_add_u32_e32 v28, 0x400, v3
	v_pk_fma_f32 v[18:19], v[12:13], v[22:23], v[18:19]
	ds_write_b32 v38, v18 offset:33536
	ds_write_b32 v39, v19 offset:33536
	ds_read_b32 v18, v54
	ds_read_b32 v19, v55
	ds_read2st64_b32 v[20:21], v40 offset0:1 offset1:2
	ds_read2st64_b32 v[22:23], v41 offset0:1 offset1:2
	ds_read_b32 v24, v40 offset:768
	ds_read_b32 v25, v41 offset:768
	s_waitcnt lgkmcnt(4)
	v_pk_fma_f32 v[18:19], v[6:7], v[18:19], v[4:5]
	s_waitcnt lgkmcnt(3)
	v_mov_b32_e32 v26, v20
	s_waitcnt lgkmcnt(2)
	v_mov_b32_e32 v27, v22
	v_mov_b32_e32 v22, v21
	v_pk_fma_f32 v[18:19], v[8:9], v[26:27], v[18:19]
	v_or_b32_e32 v43, v29, v138
	v_pk_fma_f32 v[18:19], v[10:11], v[22:23], v[18:19]
	v_or_b32_e32 v42, v28, v1
	s_waitcnt lgkmcnt(0)
	v_pk_fma_f32 v[18:19], v[12:13], v[24:25], v[18:19]
	v_lshl_add_u32 v43, v43, 2, v166
	ds_write_b32 v54, v18 offset:33536
	ds_write_b32 v55, v19 offset:33536
	v_lshl_add_u32 v29, v29, 2, v106
	v_lshl_add_u32 v28, v28, 2, v106
	v_lshl_add_u32 v42, v42, 2, v166
	ds_read_b32 v18, v43
	ds_read_b32 v19, v42
	ds_read2st64_b32 v[20:21], v29 offset0:1 offset1:2
	ds_read2st64_b32 v[22:23], v28 offset0:1 offset1:2
	ds_read_b32 v24, v29 offset:768
	ds_read_b32 v25, v28 offset:768
	s_waitcnt lgkmcnt(4)
	v_pk_fma_f32 v[18:19], v[6:7], v[18:19], v[4:5]
	s_waitcnt lgkmcnt(3)
	v_mov_b32_e32 v26, v20
	s_waitcnt lgkmcnt(2)
	v_mov_b32_e32 v27, v22
	v_mov_b32_e32 v22, v21
	v_pk_fma_f32 v[18:19], v[8:9], v[26:27], v[18:19]
	v_add_u32_e32 v31, 0x600, v17
	v_pk_fma_f32 v[18:19], v[10:11], v[22:23], v[18:19]
	v_add_u32_e32 v30, 0x600, v3
	v_or_b32_e32 v45, v31, v138
	s_waitcnt lgkmcnt(0)
	v_pk_fma_f32 v[18:19], v[12:13], v[24:25], v[18:19]
	v_or_b32_e32 v44, v30, v1
	v_lshl_add_u32 v45, v45, 2, v166
	ds_write_b32 v43, v18 offset:33536
	ds_write_b32 v42, v19 offset:33536
	v_lshl_add_u32 v31, v31, 2, v106
	v_lshl_add_u32 v30, v30, 2, v106
	v_lshl_add_u32 v44, v44, 2, v166
	ds_read_b32 v18, v45
	ds_read_b32 v19, v44
	ds_read2st64_b32 v[20:21], v31 offset0:1 offset1:2
	ds_read2st64_b32 v[22:23], v30 offset0:1 offset1:2
	ds_read_b32 v24, v31 offset:768
	ds_read_b32 v25, v30 offset:768
	s_waitcnt lgkmcnt(4)
	v_pk_fma_f32 v[18:19], v[6:7], v[18:19], v[4:5]
	s_waitcnt lgkmcnt(3)
	v_mov_b32_e32 v26, v20
	s_waitcnt lgkmcnt(2)
	v_mov_b32_e32 v27, v22
	v_mov_b32_e32 v22, v21
	v_pk_fma_f32 v[18:19], v[8:9], v[26:27], v[18:19]
	v_add_u32_e32 v33, 0x800, v17
	v_pk_fma_f32 v[18:19], v[10:11], v[22:23], v[18:19]
	v_add_u32_e32 v32, 0x800, v3
	v_or_b32_e32 v47, v33, v138
	s_waitcnt lgkmcnt(0)
	v_pk_fma_f32 v[18:19], v[12:13], v[24:25], v[18:19]
	v_or_b32_e32 v46, v32, v1
	v_lshl_add_u32 v47, v47, 2, v166
	ds_write_b32 v45, v18 offset:33536
	ds_write_b32 v44, v19 offset:33536
	v_lshl_add_u32 v33, v33, 2, v106
	v_lshl_add_u32 v32, v32, 2, v106
	v_lshl_add_u32 v46, v46, 2, v166
	ds_read_b32 v18, v47
	ds_read_b32 v19, v46
	ds_read2st64_b32 v[20:21], v33 offset0:1 offset1:2
	ds_read2st64_b32 v[22:23], v32 offset0:1 offset1:2
	ds_read_b32 v24, v33 offset:768
	ds_read_b32 v25, v32 offset:768
	s_waitcnt lgkmcnt(4)
	v_pk_fma_f32 v[18:19], v[6:7], v[18:19], v[4:5]
	s_waitcnt lgkmcnt(3)
	v_mov_b32_e32 v26, v20
	s_waitcnt lgkmcnt(2)
	v_mov_b32_e32 v27, v22
	v_mov_b32_e32 v22, v21
	v_pk_fma_f32 v[18:19], v[8:9], v[26:27], v[18:19]
	v_add_u32_e32 v35, 0xa00, v17
	v_pk_fma_f32 v[18:19], v[10:11], v[22:23], v[18:19]
	v_add_u32_e32 v34, 0xa00, v3
	v_or_b32_e32 v49, v35, v138
	s_waitcnt lgkmcnt(0)
	v_pk_fma_f32 v[18:19], v[12:13], v[24:25], v[18:19]
	v_or_b32_e32 v48, v34, v1
	v_lshl_add_u32 v49, v49, 2, v166
	ds_write_b32 v47, v18 offset:33536
	ds_write_b32 v46, v19 offset:33536
	v_lshl_add_u32 v35, v35, 2, v106
	v_lshl_add_u32 v34, v34, 2, v106
	v_lshl_add_u32 v48, v48, 2, v166
	ds_read_b32 v18, v49
	ds_read_b32 v19, v48
	ds_read2st64_b32 v[20:21], v35 offset0:1 offset1:2
	ds_read2st64_b32 v[22:23], v34 offset0:1 offset1:2
	ds_read_b32 v24, v35 offset:768
	ds_read_b32 v25, v34 offset:768
	s_waitcnt lgkmcnt(4)
	v_pk_fma_f32 v[18:19], v[6:7], v[18:19], v[4:5]
	s_waitcnt lgkmcnt(3)
	v_mov_b32_e32 v26, v20
	s_waitcnt lgkmcnt(2)
	v_mov_b32_e32 v27, v22
	v_mov_b32_e32 v22, v21
	v_pk_fma_f32 v[18:19], v[8:9], v[26:27], v[18:19]
	v_add_u32_e32 v37, 0xc00, v17
	v_pk_fma_f32 v[18:19], v[10:11], v[22:23], v[18:19]
	v_add_u32_e32 v36, 0xc00, v3
	v_or_b32_e32 v51, v37, v138
	s_waitcnt lgkmcnt(0)
; __device__ void lru_local_unit(const Params& p, unsigned char* smem, int unit) {
;     ...
; #pragma unroll 8
;     for (int tt = tid >> 6; tt < 128; tt += 4) {
;       R2[tt * 64 + j] = cb + w0 * R1[tt * 64 + j] + w1 * R1[(tt + 1) * 64 + j] + w2 * R1[(tt + 2) * 64 + j] +
;                         w3 * R1[(tt + 3) * 64 + j];
;     }
;   }
;   __syncthreads();
;   {
;     const bf16_t* waT = (const bf16_t*)(ws + OFF_WAT) + (size_t)hh * 4096;
;     const bf16_t* wxT = (const bf16_t*)(ws + OFF_WXT) + (size_t)hh * 4096;
;     f32x4 aa[2][4], ax[2][4];
; #pragma unroll
;     for (int i = 0; i < 2; ++i)
; #pragma unroll
;       for (int j = 0; j < 4; ++j) { aa[i][j] = (f32x4){0, 0, 0, 0}; ax[i][j] = (f32x4){0, 0, 0, 0}; }
; #pragma unroll
;     for (int ks = 0; ks < 2; ++ks) {
;       bf16x8 af[2];
; #pragma unroll
;       for (int mi = 0; mi < 2; ++mi) {
;         const float* src = R2 + (wid * 32 + mi * 16 + l15) * 64 + ks * 32 + q4 * 8;
;         f32x4 v0 = *(const f32x4*)src, v1 = *(const f32x4*)(src + 4);
;         u32x4 r = {pk2(v0[0], v0[1]), pk2(v0[2], v0[3]), pk2(v1[0], v1[1]), pk2(v1[2], v1[3])};
;         af[mi] = as_frag(r);
;       }
; #pragma unroll
;       for (int ni = 0; ni < 4; ++ni) {
;         const size_t wo = (size_t)(ni * 16 + l15) * 64 + ks * 32 + q4 * 8;
;         bf16x8 ba = as_frag(*(const u32x4*)(waT + wo));
;         bf16x8 bx = as_frag(*(const u32x4*)(wxT + wo));
; #pragma unroll
;         for (int mi = 0; mi < 2; ++mi) {
;           aa[mi][ni] = mfma16(af[mi], ba, aa[mi][ni]);
;           ax[mi][ni] = mfma16(af[mi], bx, ax[mi][ni]);
;         }
;       }
;     }
	v_pk_fma_f32 v[18:19], v[12:13], v[24:25], v[18:19]
	v_or_b32_e32 v50, v36, v1
	v_lshl_add_u32 v51, v51, 2, v166
	ds_write_b32 v49, v18 offset:33536
	ds_write_b32 v48, v19 offset:33536
	v_lshl_add_u32 v37, v37, 2, v106
	v_lshl_add_u32 v36, v36, 2, v106
	v_lshl_add_u32 v50, v50, 2, v166
	ds_read_b32 v18, v51
	ds_read_b32 v19, v50
	ds_read2st64_b32 v[20:21], v37 offset0:1 offset1:2
	ds_read2st64_b32 v[22:23], v36 offset0:1 offset1:2
	ds_read_b32 v24, v37 offset:768
	ds_read_b32 v25, v36 offset:768
	s_waitcnt lgkmcnt(4)
	v_pk_fma_f32 v[18:19], v[6:7], v[18:19], v[4:5]
	s_waitcnt lgkmcnt(3)
	v_mov_b32_e32 v26, v20
	s_waitcnt lgkmcnt(2)
	v_mov_b32_e32 v27, v22
	v_mov_b32_e32 v22, v21
	v_pk_fma_f32 v[18:19], v[8:9], v[26:27], v[18:19]
	v_add_u32_e32 v17, 0xe00, v17
	v_pk_fma_f32 v[18:19], v[10:11], v[22:23], v[18:19]
	v_add_u32_e32 v3, 0xe00, v3
	v_or_b32_e32 v53, v17, v138
	s_waitcnt lgkmcnt(0)
	v_pk_fma_f32 v[18:19], v[12:13], v[24:25], v[18:19]
	v_or_b32_e32 v52, v3, v1
	v_lshl_add_u32 v53, v53, 2, v166
	ds_write_b32 v51, v18 offset:33536
	ds_write_b32 v50, v19 offset:33536
	v_lshl_add_u32 v17, v17, 2, v106
	v_lshl_add_u32 v3, v3, 2, v106
	v_lshl_add_u32 v52, v52, 2, v166
	ds_read_b32 v18, v53
	ds_read_b32 v19, v52
	ds_read2st64_b32 v[20:21], v17 offset0:1 offset1:2
	ds_read2st64_b32 v[22:23], v3 offset0:1 offset1:2
	ds_read_b32 v24, v17 offset:768
	ds_read_b32 v25, v3 offset:768
	s_waitcnt lgkmcnt(4)
	v_pk_fma_f32 v[18:19], v[6:7], v[18:19], v[4:5]
	s_waitcnt lgkmcnt(3)
	v_mov_b32_e32 v26, v20
	s_waitcnt lgkmcnt(2)
	v_mov_b32_e32 v27, v22
	v_mov_b32_e32 v22, v21
	v_pk_fma_f32 v[18:19], v[8:9], v[26:27], v[18:19]
	s_add_i32 s12, s12, -16
	v_pk_fma_f32 v[18:19], v[10:11], v[22:23], v[18:19]
	v_add_u32_e32 v15, 64, v15
	v_add_u32_e32 v14, 64, v14
	s_cmp_eq_u32 s12, 0
	s_waitcnt lgkmcnt(0)
	v_pk_fma_f32 v[18:19], v[12:13], v[24:25], v[18:19]
	ds_write_b32 v53, v18 offset:33536
	ds_write_b32 v52, v19 offset:33536
	s_cbranch_scc0 .LBB0_530
	v_lshlrev_b32_e32 v68, 13, v16
	v_lshl_add_u64 v[4:5], s[14:15], 0, v[68:69]
	v_lshl_add_u64 v[6:7], s[10:11], 0, v[68:69]
	v_lshl_add_u64 v[44:45], v[4:5], 0, v[82:83]
	v_lshl_add_u64 v[52:53], v[6:7], 0, v[82:83]
	s_waitcnt lgkmcnt(0)
	s_barrier
	v_mov_b64 v[8:9], v[216:217]
	v_mov_b64 v[10:11], v[218:219]
	v_mov_b64 v[12:13], v[220:221]
	v_mov_b64 v[14:15], v[222:223]
	ds_read_b128 v[16:19], v107 offset:33536
	ds_read_b128 v[20:23], v107 offset:33552
	ds_read_b128 v[24:27], v107 offset:37632
	ds_read_b128 v[32:35], v107 offset:37648
	v_mov_b64 v[28:29], v[224:225]
	v_mov_b64 v[30:31], v[226:227]
	v_mov_b64 v[36:37], v[228:229]
	v_mov_b64 v[38:39], v[230:231]
	s_waitcnt lgkmcnt(1)
	v_cvt_pk_bf16_f32 v24, v24, v25
	v_cvt_pk_bf16_f32 v25, v26, v27
	s_waitcnt lgkmcnt(0)
	v_cvt_pk_bf16_f32 v26, v32, v33
	v_cvt_pk_bf16_f32 v27, v34, v35
	v_mov_b64 v[32:33], v[232:233]
	v_mov_b64 v[34:35], v[234:235]
	v_mov_b64 v[94:95], v[236:237]
	v_mov_b64 v[96:97], v[238:239]
	v_mov_b64 v[48:49], v[240:241]
	v_mov_b64 v[50:51], v[242:243]
	v_mov_b64 v[98:99], v[244:245]
	v_mov_b64 v[100:101], v[246:247]
	v_lshl_add_u64 v[52:53], v[4:5], 0, v[84:85]
	global_load_dwordx4 v[52:55], v[52:53], off
	v_lshl_add_u64 v[56:57], v[6:7], 0, v[84:85]
	v_cvt_pk_bf16_f32 v16, v16, v17
	v_cvt_pk_bf16_f32 v17, v18, v19
	v_cvt_pk_bf16_f32 v18, v20, v21
	v_cvt_pk_bf16_f32 v19, v22, v23
	v_or_b32_e32 v3, v128, v105
	v_lshlrev_b32_e32 v3, 2, v3
	global_load_dword v68, v3, s[54:55]
	v_lshl_add_u64 v[64:65], v[4:5], 0, v[88:89]
	s_mov_b32 s66, 0
	s_waitcnt vmcnt(9)
	v_mfma_f32_16x16x32_bf16 v[20:23], v[16:19], v[8:11], 0
	s_waitcnt vmcnt(3)
	v_mfma_f32_16x16x32_bf16 v[130:133], v[16:19], v[48:51], 0
	v_mfma_f32_16x16x32_bf16 v[134:137], v[24:27], v[48:51], 0
	global_load_dwordx4 v[48:51], v[56:57], off
	v_lshl_add_u64 v[56:57], v[4:5], 0, v[86:87]
	v_lshl_add_u64 v[4:5], v[4:5], 0, v[90:91]
	s_waitcnt vmcnt(2)
	v_mfma_f32_16x16x32_bf16 v[140:143], v[16:19], v[52:55], 0
	v_mfma_f32_16x16x32_bf16 v[148:151], v[24:27], v[52:55], 0
	global_load_dwordx4 v[52:55], v[56:57], off
	v_lshl_add_u64 v[56:57], v[6:7], 0, v[86:87]
	v_mfma_f32_16x16x32_bf16 v[8:11], v[24:27], v[8:11], 0
	v_mfma_f32_16x16x32_bf16 v[40:43], v[16:19], v[12:15], 0
	v_mfma_f32_16x16x32_bf16 v[12:15], v[24:27], v[12:15], 0
	v_mfma_f32_16x16x32_bf16 v[44:47], v[16:19], v[32:35], 0
	v_mfma_f32_16x16x32_bf16 v[32:35], v[24:27], v[32:35], 0
	s_waitcnt vmcnt(1)
	v_mfma_f32_16x16x32_bf16 v[144:147], v[16:19], v[48:51], 0
	v_mfma_f32_16x16x32_bf16 v[152:155], v[24:27], v[48:51], 0
	global_load_dwordx4 v[48:51], v[56:57], off
	ds_read_b128 v[56:59], v107 offset:33664
	ds_read_b128 v[60:63], v107 offset:33680
	ds_read_b128 v[160:163], v107 offset:37760
	s_waitcnt vmcnt(1)
	v_mfma_f32_16x16x32_bf16 v[156:159], v[16:19], v[52:55], 0
	global_load_dwordx4 v[168:171], v[64:65], off
	s_waitcnt lgkmcnt(2)
	v_cvt_pk_bf16_f32 v180, v56, v57
	v_cvt_pk_bf16_f32 v181, v58, v59
	v_mfma_f32_16x16x32_bf16 v[172:175], v[24:27], v[52:55], 0
	v_lshl_add_u64 v[52:53], v[6:7], 0, v[88:89]
	global_load_dwordx4 v[176:179], v[52:53], off
	s_waitcnt lgkmcnt(1)
	v_cvt_pk_bf16_f32 v182, v60, v61
	v_cvt_pk_bf16_f32 v183, v62, v63
	s_waitcnt vmcnt(2)
	v_mfma_f32_16x16x32_bf16 v[16:19], v[16:19], v[48:51], 0
	v_mfma_f32_16x16x32_bf16 v[60:63], v[180:183], v[28:31], v[20:23]
	s_nop 2
	ds_read_b128 v[20:23], v107 offset:37776
	s_waitcnt lgkmcnt(1)
	v_cvt_pk_bf16_f32 v160, v160, v161
	v_cvt_pk_bf16_f32 v161, v162, v163
	s_waitcnt lgkmcnt(0)
; __device__ __forceinline__ float sigmoid_(float x) { return __builtin_amdgcn_rcpf(1.f + __expf(-x)); }
; __device__ void lru_local_unit(const Params& p, unsigned char* smem, int unit) {
;     ...
; #pragma unroll
;     for (int ni = 0; ni < 4; ++ni) {
;       const int j = ni * 16 + l15;
;       const float ba = p.lru_ba[ch0 + j], bx = p.lru_bx[ch0 + j];
;       const float lam = p.lru_lambda[ch0 + j];
;       const float spl = -8.f * log1pf(__expf(-lam));
; #pragma unroll
;       for (int mi = 0; mi < 2; ++mi)
; #pragma unroll
;         for (int r = 0; r < 4; ++r) {
;           const int tt = wid * 32 + mi * 16 + q4 * 4 + r;
;           const float rg = sigmoid_(aa[mi][ni][r] + ba);
;           const float ig = sigmoid_(ax[mi][ni][r] + bx);
;           const float log_a = spl * rg;
;           const float av = __expf(log_a);
	v_cvt_pk_bf16_f32 v162, v20, v21
	v_cvt_pk_bf16_f32 v163, v22, v23
	v_mfma_f32_16x16x32_bf16 v[44:47], v[180:183], v[94:97], v[44:47]
	v_mfma_f32_16x16x32_bf16 v[52:55], v[160:163], v[28:31], v[8:11]
	s_nop 2
	global_load_dwordx4 v[8:11], v[4:5], off
	v_lshl_add_u64 v[4:5], v[6:7], 0, v[90:91]
	global_load_dwordx4 v[188:191], v[4:5], off
	global_load_dword v167, v3, s[48:49]
	global_load_dword v192, v3, s[52:53]
	v_mul_f32_e32 v4, 0xbfb8aa3b, v68
	v_exp_f32_e32 v68, v4
	v_mfma_f32_16x16x32_bf16 v[64:67], v[180:183], v[36:39], v[40:43]
	v_add_f32_e32 v3, 1.0, v68
	v_add_f32_e32 v4, -1.0, v3
	v_sub_f32_e32 v5, v4, v3
	v_add_f32_e32 v5, 1.0, v5
	v_sub_f32_e32 v4, v68, v4
	v_add_f32_e32 v6, v4, v5
	v_frexp_mant_f32_e32 v7, v3
	v_cvt_f64_f32_e32 v[4:5], v3
	v_frexp_exp_i32_f64_e32 v4, v[4:5]
	v_cmp_gt_f32_e32 vcc, s90, v7
	v_mfma_f32_16x16x32_bf16 v[56:59], v[160:163], v[36:39], v[12:15]
	s_waitcnt vmcnt(1)
	v_add_f32_e32 v62, v62, v167
	v_subbrev_co_u32_e32 v102, vcc, 0, v4, vcc
	v_sub_u32_e32 v4, 0, v102
	v_ldexp_f32 v3, v3, v4
	v_add_f32_e32 v93, -1.0, v3
	v_add_f32_e32 v5, 1.0, v93
	v_ldexp_f32 v4, v6, v4
	v_sub_f32_e32 v5, v3, v5
	v_mfma_f32_16x16x32_bf16 v[36:39], v[160:163], v[94:97], v[32:35]
	v_add_f32_e32 v94, v4, v5
	v_add_f32_e32 v5, 1.0, v3
	v_add_f32_e32 v6, -1.0, v5
	v_sub_f32_e32 v3, v3, v6
	v_add_f32_e32 v3, v4, v3
	v_add_f32_e32 v103, v5, v3
	v_rcp_f32_e32 v129, v103
	v_add_f32_e32 v95, v93, v94
	v_mfma_f32_16x16x32_bf16 v[184:187], v[24:27], v[48:51], 0
	v_sub_f32_e32 v4, v103, v5
	v_sub_f32_e32 v3, v3, v4
	v_mul_f32_e32 v62, 0xbfb8aa3b, v62
	v_mfma_f32_16x16x32_bf16 v[48:51], v[180:183], v[98:101], v[130:133]
	s_waitcnt vmcnt(0)
	v_add_f32_e32 v66, v66, v192
	v_exp_f32_e32 v62, v62
	v_mul_f32_e32 v66, 0xbfb8aa3b, v66
	v_mul_f32_e32 v130, v95, v129
	v_mul_f32_e32 v96, v103, v130
	v_mfma_f32_16x16x32_bf16 v[40:43], v[160:163], v[98:101], v[134:137]
	v_fma_f32 v98, v130, v103, -v96
	v_fmac_f32_e32 v98, v130, v3
	v_exp_f32_e32 v66, v66
	v_mfma_f32_16x16x32_bf16 v[12:15], v[180:183], v[8:11], v[156:159]
	v_add_f32_e32 v52, v52, v167
	v_mul_f32_e32 v52, 0xbfb8aa3b, v52
	v_add_f32_e32 v56, v56, v192
	v_mfma_f32_16x16x32_bf16 v[4:7], v[160:163], v[8:11], v[172:175]
	v_sub_f32_e32 v8, v95, v93
	v_sub_f32_e32 v93, v94, v8
	v_add_f32_e32 v94, v96, v98
	v_sub_f32_e32 v97, v95, v94
	v_pk_add_f32 v[100:101], v[94:95], v[96:97] neg_lo:[0,1] neg_hi:[0,1]
	v_mov_b32_e32 v99, v94
	v_pk_add_f32 v[94:95], v[100:101], v[98:99] neg_lo:[0,1] neg_hi:[0,1]
	v_exp_f32_e32 v52, v52
	v_add_f32_e32 v93, v93, v95
	v_add_f32_e32 v93, v94, v93
	v_add_f32_e32 v95, v97, v93
	v_mul_f32_e32 v131, v129, v95
	v_mul_f32_e32 v96, v103, v131
	v_fma_f32 v98, v131, v103, -v96
	v_fmac_f32_e32 v98, v131, v3
	v_add_f32_e32 v94, v96, v98
	v_sub_f32_e32 v3, v97, v95
	v_sub_f32_e32 v97, v95, v94
	v_pk_add_f32 v[100:101], v[94:95], v[96:97] neg_lo:[0,1] neg_hi:[0,1]
	v_mov_b32_e32 v99, v94
	v_add_f32_e32 v3, v93, v3
	v_pk_add_f32 v[94:95], v[100:101], v[98:99] neg_lo:[0,1] neg_hi:[0,1]
	v_mul_f32_e32 v56, 0xbfb8aa3b, v56
	v_add_f32_e32 v3, v3, v95
	v_add_f32_e32 v3, v94, v3
	v_add_f32_e32 v95, v130, v131
	v_add_f32_e32 v3, v97, v3
	v_sub_f32_e32 v93, v95, v130
	v_mul_f32_e32 v3, v129, v3
	v_sub_f32_e32 v93, v131, v93
	v_add_f32_e32 v3, v93, v3
	v_add_f32_e32 v96, v95, v3
	v_cvt_f32_i32_e32 v94, v102
	v_mul_f32_e32 v97, v96, v96
	v_fmamk_f32 v93, v97, 0x3e9b6dac, v121
	v_sub_f32_e32 v95, v96, v95
	v_fmaak_f32 v93, v97, v93, 0x3f2aaada
	v_sub_f32_e32 v3, v3, v95
	v_mul_f32_e32 v95, v96, v97
	v_ldexp_f32 v99, v96, 1
	v_pk_mul_f32 v[96:97], v[94:95], v[92:93]
	v_ldexp_f32 v3, v3, 1
	v_fma_f32 v98, v94, s91, -v96
	v_fmac_f32_e32 v98, 0xb102e308, v94
	v_pk_add_f32 v[94:95], v[96:97], v[98:99]
	v_mov_b32_e32 v100, v96
	v_sub_f32_e32 v93, v95, v99
	v_sub_f32_e32 v93, v97, v93
	v_add_f32_e32 v101, v3, v93
	v_add_f32_e32 v3, v60, v167
	v_mul_f32_e32 v3, 0xbfb8aa3b, v3
	v_add_f32_e32 v60, v64, v192
	v_exp_f32_e32 v3, v3
	v_mul_f32_e32 v60, 0xbfb8aa3b, v60
	v_exp_f32_e32 v64, v60
	v_pk_add_f32 v[102:103], v[94:95], v[96:97] neg_lo:[0,1] neg_hi:[0,1]
	v_add_f32_e32 v3, 1.0, v3
	v_rcp_f32_e32 v60, v3
	v_add_f32_e32 v3, 1.0, v64
	v_rcp_f32_e32 v64, v3
	v_add_f32_e32 v3, v61, v167
	v_mul_f32_e32 v3, 0xbfb8aa3b, v3
	v_exp_f32_e32 v61, v3
	v_add_f32_e32 v3, v65, v192
	v_mul_f32_e32 v65, 0xbfb8aa3b, v3
	v_add_lshl_u32 v3, v128, v105, 2
	global_load_dword v93, v3, s[54:55] offset:64
	v_pk_add_f32 v[130:131], v[94:95], v[100:101]
	v_mov_b32_e32 v99, v94
	v_mov_b32_e32 v103, v131
	v_pk_add_f32 v[96:97], v[98:99], v[102:103] neg_lo:[0,1] neg_hi:[0,1]
	v_pk_add_f32 v[98:99], v[98:99], v[102:103]
	v_mov_b32_e32 v100, v101
	v_pk_add_f32 v[102:103], v[98:99], v[94:95] op_sel:[1,0] op_sel_hi:[0,1] neg_lo:[0,1] neg_hi:[0,1]
	v_pk_add_f32 v[132:133], v[130:131], v[102:103] op_sel_hi:[1,0] neg_lo:[0,1] neg_hi:[0,1]
	v_pk_mov_b32 v[102:103], v[94:95], v[102:103] op_sel:[1,0]
	v_mov_b32_e32 v101, v94
	ds_read2_b32 v[94:95], v123 offset0:192 offset1:208
	v_exp_f32_e32 v65, v65
	v_add_f32_e32 v61, 1.0, v61
	v_mov_b32_e32 v98, v131
	v_rcp_f32_e32 v131, v61
	s_waitcnt lgkmcnt(0)
	v_mul_f32_e32 v94, v94, v64
	v_add_f32_e32 v61, 1.0, v65
	ds_read2st64_b32 v[64:65], v108 offset0:132 offset1:133
	v_rcp_f32_e32 v61, v61
	v_exp_f32_e32 v56, v56
	v_pk_add_f32 v[102:103], v[98:99], v[102:103] neg_lo:[0,1] neg_hi:[0,1]
	v_mov_b32_e32 v132, v96
	s_waitcnt lgkmcnt(0)
; __device__ __forceinline__ float sigmoid_(float x) { return __builtin_amdgcn_rcpf(1.f + __expf(-x)); }
; __device__ void lru_local_unit(const Params& p, unsigned char* smem, int unit) {
;     ...
; #pragma unroll
;     for (int ni = 0; ni < 4; ++ni) {
;       const int j = ni * 16 + l15;
;       const float ba = p.lru_ba[ch0 + j], bx = p.lru_bx[ch0 + j];
;       const float lam = p.lru_lambda[ch0 + j];
;       const float spl = -8.f * log1pf(__expf(-lam));
; #pragma unroll
;       for (int mi = 0; mi < 2; ++mi)
; #pragma unroll
;         for (int r = 0; r < 4; ++r) {
;           const int tt = wid * 32 + mi * 16 + q4 * 4 + r;
;           const float rg = sigmoid_(aa[mi][ni][r] + ba);
;           const float ig = sigmoid_(ax[mi][ni][r] + bx);
;           const float log_a = spl * rg;
;           const float av = __expf(log_a);
;           const float xl = R2[tt * 64 + j];
;           const float y2 = 2.f * log_a;
;           const float poly = -y2 * (1.f + y2 * (0.5f + y2 * (0.16666667f + y2 * (0.041666668f + y2 * (0.0083333338f + y2 * 0.0013888889f)))));
;           const float em = (y2 > -0.25f) ? poly : (1.f - av * av);
;           const float bv = __builtin_amdgcn_sqrtf(fmaxf(em, 0.f)) * (ig * xl);
;           R1[tt * 64 + j] = av;
;           R2[tt * 64 + j] = bv;
;         }
	v_mul_f32_e32 v129, v64, v61
	v_add_f32_e32 v61, 1.0, v62
	v_add_f32_e32 v62, v63, v167
	v_rcp_f32_e32 v130, v61
	v_add_f32_e32 v61, 1.0, v66
	v_mul_f32_e32 v62, 0xbfb8aa3b, v62
	v_add_f32_e32 v63, v67, v192
	v_rcp_f32_e32 v61, v61
	v_exp_f32_e32 v62, v62
	v_mul_f32_e32 v63, 0xbfb8aa3b, v63
	v_exp_f32_e32 v63, v63
	v_pk_add_f32 v[100:101], v[100:101], v[102:103] neg_lo:[0,1] neg_hi:[0,1]
	v_mul_f32_e32 v64, v61, v65
	v_add_f32_e32 v61, 1.0, v62
	v_add_f32_e32 v52, 1.0, v52
	v_add_f32_e32 v53, v53, v167
	v_pk_add_f32 v[102:103], v[132:133], v[100:101]
	ds_read2st64_b32 v[132:133], v108 offset0:148 offset1:149
	ds_read_b32 v98, v108 offset:38400
	v_rcp_f32_e32 v128, v61
	v_add_f32_e32 v61, 1.0, v63
	ds_read2st64_b32 v[62:63], v108 offset0:134 offset1:147
	v_rcp_f32_e32 v67, v52
	v_add_f32_e32 v52, 1.0, v56
	v_mul_f32_e32 v53, 0xbfb8aa3b, v53
	v_add_f32_e32 v56, v57, v192
	v_rcp_f32_e32 v61, v61
	v_rcp_f32_e32 v52, v52
	v_exp_f32_e32 v53, v53
	v_mul_f32_e32 v56, 0xbfb8aa3b, v56
	v_exp_f32_e32 v56, v56
	s_waitcnt lgkmcnt(0)
	v_mul_f32_e32 v66, v61, v62
	v_mul_f32_e32 v61, v52, v63
	v_add_f32_e32 v52, 1.0, v53
	v_add_f32_e32 v53, v54, v167
	v_rcp_f32_e32 v65, v52
	v_add_f32_e32 v52, 1.0, v56
	v_mul_f32_e32 v53, 0xbfb8aa3b, v53
	v_add_f32_e32 v54, v58, v192
	v_rcp_f32_e32 v52, v52
	v_exp_f32_e32 v53, v53
	v_mul_f32_e32 v54, 0xbfb8aa3b, v54
	v_exp_f32_e32 v54, v54
	v_mul_f32_e32 v62, v52, v132
	v_add_f32_e32 v52, 1.0, v53
	v_rcp_f32_e32 v63, v52
	v_add_f32_e32 v52, 1.0, v54
	v_rcp_f32_e32 v52, v52
	v_add_f32_e32 v53, v55, v167
	v_mul_f32_e32 v53, 0xbfb8aa3b, v53
	v_add_f32_e32 v54, v59, v192
	v_exp_f32_e32 v53, v53
	v_mul_f32_e32 v54, 0xbfb8aa3b, v54
	v_mfma_f32_16x16x32_bf16 v[20:23], v[160:163], v[168:171], v[148:151]
	v_exp_f32_e32 v54, v54
	v_mul_f32_e32 v59, v52, v133
	global_load_dword v58, v3, s[52:53] offset:128
	global_load_dword v133, v3, s[54:55] offset:128
	global_load_dword v56, v3, s[52:53] offset:192
	global_load_dword v150, v3, s[52:53] offset:64
	global_load_dword v151, v3, s[48:49] offset:64
	v_add_f32_e32 v52, 1.0, v53
	v_rcp_f32_e32 v53, v52
	v_add_f32_e32 v52, 1.0, v54
	s_waitcnt vmcnt(5)
	v_mul_f32_e32 v54, 0xbfb8aa3b, v93
	v_rcp_f32_e32 v52, v52
	v_exp_f32_e32 v148, v54
	v_mfma_f32_16x16x32_bf16 v[28:31], v[180:183], v[168:171], v[140:143]
	v_mov_b32_e32 v97, v99
	v_mul_f32_e32 v149, v52, v98
	v_add_f32_e32 v52, 1.0, v148
	v_add_f32_e32 v54, -1.0, v52
	v_sub_f32_e32 v55, v54, v52
	v_add_f32_e32 v55, 1.0, v55
	v_sub_f32_e32 v54, v148, v54
	v_add_f32_e32 v57, v54, v55
	v_frexp_mant_f32_e32 v93, v52
	v_cvt_f64_f32_e32 v[54:55], v52
	v_frexp_exp_i32_f64_e32 v54, v[54:55]
	v_cmp_gt_f32_e32 vcc, s90, v93
	v_mfma_f32_16x16x32_bf16 v[32:35], v[180:183], v[176:179], v[144:147]
	s_waitcnt vmcnt(1)
	v_add_f32_e32 v40, v40, v150
	v_subbrev_co_u32_e32 v98, vcc, 0, v54, vcc
	v_sub_u32_e32 v54, 0, v98
	v_ldexp_f32 v52, v52, v54
	v_ldexp_f32 v54, v57, v54
	v_add_f32_e32 v57, -1.0, v52
	v_add_f32_e32 v55, 1.0, v57
	v_sub_f32_e32 v55, v52, v55
	v_add_f32_e32 v93, v54, v55
	v_add_f32_e32 v55, 1.0, v52
	v_add_f32_e32 v101, -1.0, v55
	v_sub_f32_e32 v52, v52, v101
	v_add_f32_e32 v52, v54, v52
	v_add_f32_e32 v101, v55, v52
	v_rcp_f32_e32 v132, v101
	v_sub_f32_e32 v54, v101, v55
	v_add_f32_e32 v55, v57, v93
	v_sub_f32_e32 v52, v52, v54
	v_sub_f32_e32 v54, v55, v57
	v_sub_f32_e32 v57, v93, v54
	v_mul_f32_e32 v93, v55, v132
	v_mul_f32_e32 v134, v101, v93
	v_fma_f32 v136, v93, v101, -v134
	v_fmac_f32_e32 v136, v93, v52
	v_add_f32_e32 v54, v134, v136
	v_sub_f32_e32 v135, v55, v54
	v_pk_add_f32 v[140:141], v[54:55], v[134:135] neg_lo:[0,1] neg_hi:[0,1]
	v_mov_b32_e32 v137, v54
	v_pk_add_f32 v[54:55], v[140:141], v[136:137] neg_lo:[0,1] neg_hi:[0,1]
	s_waitcnt vmcnt(0)
	v_add_f32_e32 v44, v44, v151
	v_add_f32_e32 v55, v57, v55
	v_add_f32_e32 v54, v54, v55
	v_add_f32_e32 v55, v135, v54
	v_mul_f32_e32 v57, v132, v55
	v_mul_f32_e32 v134, v101, v57
	v_fma_f32 v136, v57, v101, -v134
	v_fmac_f32_e32 v136, v57, v52
	v_sub_f32_e32 v52, v135, v55
	v_add_f32_e32 v52, v54, v52
	v_add_f32_e32 v54, v134, v136
	v_sub_f32_e32 v135, v55, v54
	v_pk_add_f32 v[140:141], v[54:55], v[134:135] neg_lo:[0,1] neg_hi:[0,1]
	v_mov_b32_e32 v137, v54
	v_pk_add_f32 v[54:55], v[140:141], v[136:137] neg_lo:[0,1] neg_hi:[0,1]
	v_mul_f32_e32 v44, 0xbfb8aa3b, v44
	v_add_f32_e32 v52, v52, v55
	v_add_f32_e32 v52, v54, v52
	v_add_f32_e32 v55, v93, v57
	v_add_f32_e32 v52, v135, v52
	v_sub_f32_e32 v54, v55, v93
	v_mul_f32_e32 v52, v132, v52
	v_sub_f32_e32 v54, v57, v54
	v_add_f32_e32 v52, v54, v52
	v_add_f32_e32 v57, v55, v52
	v_mul_f32_e32 v101, v57, v57
	v_fmamk_f32 v54, v101, 0x3e9b6dac, v121
	v_fmaak_f32 v93, v101, v54, 0x3f2aaada
	v_cvt_f32_i32_e32 v54, v98
	v_sub_f32_e32 v55, v57, v55
	v_sub_f32_e32 v52, v52, v55
	v_mul_f32_e32 v55, v57, v101
	v_pk_mul_f32 v[136:137], v[54:55], v[92:93]
	v_ldexp_f32 v135, v57, 1
	v_fma_f32 v134, v54, s91, -v136
	v_fmac_f32_e32 v134, 0xb102e308, v54
	v_pk_add_f32 v[54:55], v[136:137], v[134:135]
	v_ldexp_f32 v52, v52, 1
	v_sub_f32_e32 v57, v55, v135
	v_sub_f32_e32 v57, v137, v57
	v_add_f32_e32 v141, v52, v57
	v_mov_b32_e32 v140, v136
	v_pk_add_f32 v[136:137], v[54:55], v[136:137] neg_lo:[0,1] neg_hi:[0,1]
	v_pk_add_f32 v[142:143], v[54:55], v[140:141]
	v_mov_b32_e32 v135, v54
	v_mov_b32_e32 v137, v143
	v_pk_add_f32 v[144:145], v[134:135], v[136:137] neg_lo:[0,1] neg_hi:[0,1]
	v_pk_add_f32 v[134:135], v[134:135], v[136:137]
	v_mov_b32_e32 v140, v141
	v_pk_add_f32 v[136:137], v[134:135], v[54:55] op_sel:[1,0] op_sel_hi:[0,1] neg_lo:[0,1] neg_hi:[0,1]
	v_pk_add_f32 v[146:147], v[142:143], v[136:137] op_sel_hi:[1,0] neg_lo:[0,1] neg_hi:[0,1]
; __device__ __forceinline__ float sigmoid_(float x) { return __builtin_amdgcn_rcpf(1.f + __expf(-x)); }
; __device__ void lru_local_unit(const Params& p, unsigned char* smem, int unit) {
;     ...
; #pragma unroll
;     for (int ni = 0; ni < 4; ++ni) {
;       const int j = ni * 16 + l15;
;       const float ba = p.lru_ba[ch0 + j], bx = p.lru_bx[ch0 + j];
;       const float lam = p.lru_lambda[ch0 + j];
;       const float spl = -8.f * log1pf(__expf(-lam));
; #pragma unroll
;       for (int mi = 0; mi < 2; ++mi)
; #pragma unroll
;         for (int r = 0; r < 4; ++r) {
;           const int tt = wid * 32 + mi * 16 + q4 * 4 + r;
;           const float rg = sigmoid_(aa[mi][ni][r] + ba);
;           const float ig = sigmoid_(ax[mi][ni][r] + bx);
;           const float log_a = spl * rg;
;           const float av = __expf(log_a);
;           const float xl = R2[tt * 64 + j];
;           const float y2 = 2.f * log_a;
;           const float poly = -y2 * (1.f + y2 * (0.5f + y2 * (0.16666667f + y2 * (0.041666668f + y2 * (0.0083333338f + y2 * 0.0013888889f)))));
;           const float em = (y2 > -0.25f) ? poly : (1.f - av * av);
;           const float bv = __builtin_amdgcn_sqrtf(fmaxf(em, 0.f)) * (ig * xl);
;           R1[tt * 64 + j] = av;
;           R2[tt * 64 + j] = bv;
;         }
	v_mov_b32_e32 v134, v143
	v_pk_mov_b32 v[136:137], v[54:55], v[136:137] op_sel:[1,0]
	v_mov_b32_e32 v141, v54
	v_pk_add_f32 v[136:137], v[134:135], v[136:137] neg_lo:[0,1] neg_hi:[0,1]
	v_mov_b32_e32 v146, v144
	v_pk_add_f32 v[54:55], v[140:141], v[136:137] neg_lo:[0,1] neg_hi:[0,1]
	v_mov_b32_e32 v141, v102
	v_pk_add_f32 v[136:137], v[146:147], v[54:55]
	v_mov_b32_e32 v143, v103
	v_mov_b32_e32 v140, v136
	v_mov_b32_e32 v142, v137
	v_pk_add_f32 v[142:143], v[140:141], v[142:143]
	v_mov_b32_e32 v98, v135
	v_pk_add_f32 v[98:99], v[98:99], v[142:143]
	v_mov_b32_e32 v145, v135
	v_mov_b32_e32 v103, v99
	v_mov_b32_e32 v137, v98
	v_pk_add_f32 v[102:103], v[102:103], v[96:97] neg_lo:[0,1] neg_hi:[0,1]
	v_pk_add_f32 v[134:135], v[136:137], v[144:145] neg_lo:[0,1] neg_hi:[0,1]
	v_mov_b32_e32 v101, v143
	v_mov_b32_e32 v136, v134
	v_mov_b32_e32 v137, v102
	v_mov_b32_e32 v55, v142
	v_exp_f32_e32 v44, v44
	v_pk_add_f32 v[100:101], v[100:101], v[102:103] neg_lo:[0,1] neg_hi:[0,1]
	v_pk_add_f32 v[102:103], v[140:141], v[136:137] neg_lo:[0,1] neg_hi:[0,1]
	v_mov_b32_e32 v145, v96
	v_pk_add_f32 v[54:55], v[54:55], v[134:135] neg_lo:[0,1] neg_hi:[0,1]
	v_pk_add_f32 v[96:97], v[144:145], v[102:103] neg_lo:[0,1] neg_hi:[0,1]
	v_mov_b32_e32 v102, v54
	v_mov_b32_e32 v103, v100
	v_pk_add_f32 v[96:97], v[102:103], v[96:97]
	v_mov_b32_e32 v100, v55
	v_pk_add_f32 v[54:55], v[96:97], v[100:101]
	v_add_f32_e32 v44, 1.0, v44
	v_pk_add_f32 v[54:55], v[98:99], v[54:55]
	v_cmp_neq_f32_e32 vcc, s92, v148
	v_rcp_f32_e32 v52, v44
	v_add_f32_e32 v44, v48, v150
	v_cndmask_b32_e32 v48, v124, v54, vcc
	v_cmp_neq_f32_e32 vcc, s92, v68
	global_load_dword v132, v3, s[48:49] offset:128
	global_load_dword v57, v3, s[48:49] offset:192
	v_cndmask_b32_e32 v54, v124, v55, vcc
	v_cmp_ngt_f32_e32 vcc, -1.0, v68
	v_mul_f32_e32 v44, 0xbfb8aa3b, v44
	v_exp_f32_e32 v44, v44
	v_cndmask_b32_e32 v54, v125, v54, vcc
	v_cmp_ngt_f32_e32 vcc, -1.0, v148
	v_add_f32_e32 v45, v45, v151
	v_mul_f32_e32 v45, 0xbfb8aa3b, v45
	v_cndmask_b32_e32 v48, v125, v48, vcc
	v_cmp_neq_f32_e32 vcc, -1.0, v148
	v_exp_f32_e32 v45, v45
	v_add_f32_e32 v44, 1.0, v44
	v_cndmask_b32_e32 v48, v126, v48, vcc
	v_cmp_neq_f32_e32 vcc, -1.0, v68
	v_rcp_f32_e32 v44, v44
	v_add_f32_e32 v45, 1.0, v45
	v_cndmask_b32_e32 v54, v126, v54, vcc
	v_cmp_lt_f32_e64 vcc, |v68|, s93
	v_rcp_f32_e32 v45, v45
	v_mul_f32_e32 v44, v95, v44
	v_cndmask_b32_e32 v55, v54, v68, vcc
	v_cmp_lt_f32_e64 vcc, |v148|, s93
	v_add_f32_e32 v46, v46, v151
	v_mul_f32_e32 v46, 0xbfb8aa3b, v46
	v_cndmask_b32_e32 v54, v48, v148, vcc
	v_pk_mul_f32 v[54:55], v[54:55], s[38:39] op_sel_hi:[1,0]
	v_exp_f32_e32 v46, v46
	v_mul_f32_e32 v48, v60, v55
	v_mul_f32_e32 v60, 0x3fb8aa3b, v48
	v_add_f32_e32 v48, v48, v48
	v_exp_f32_e32 v68, v60
	v_fmamk_f32 v60, v48, 0x3ab60b61, v122
	v_fmaak_f32 v60, v48, v60, 0x3d2aaaab
	v_fmaak_f32 v60, v48, v60, 0x3e2aaaab
	v_fma_f32 v60, v48, v60, 0.5
	v_fma_f32 v60, v48, v60, 1.0
	v_mul_f32_e64 v60, v60, -v48
	v_fma_f32 v93, -v68, v68, 1.0
	v_cmp_lt_f32_e32 vcc, s94, v48
	v_mul_f32_e32 v65, v65, v55
	v_pk_mul_f32 v[52:53], v[52:53], v[54:55]
	v_cndmask_b32_e32 v48, v93, v60, vcc
	v_mul_f32_e32 v60, v131, v55
	v_mul_f32_e32 v93, 0x3fb8aa3b, v60
	v_add_f32_e32 v60, v60, v60
	v_max_f32_e32 v48, 0, v48
	v_fmamk_f32 v96, v60, 0x3ab60b61, v122
	v_sqrt_f32_e32 v48, v48
	v_exp_f32_e32 v93, v93
	v_fmaak_f32 v96, v60, v96, 0x3d2aaaab
	v_fmaak_f32 v96, v60, v96, 0x3e2aaaab
	v_fma_f32 v96, v60, v96, 0.5
	v_fma_f32 v96, v60, v96, 1.0
	v_mul_f32_e64 v96, v96, -v60
	v_fma_f32 v97, -v93, v93, 1.0
	v_cmp_lt_f32_e32 vcc, s94, v60
	v_mul_f32_e32 v48, v94, v48
	v_mul_f32_e32 v94, v130, v55
	v_cndmask_b32_e32 v60, v97, v96, vcc
	v_mul_f32_e32 v96, 0x3fb8aa3b, v94
	v_add_f32_e32 v94, v94, v94
	v_fmamk_f32 v97, v94, 0x3ab60b61, v122
	v_exp_f32_e32 v96, v96
	v_fmaak_f32 v97, v94, v97, 0x3d2aaaab
	v_fmaak_f32 v97, v94, v97, 0x3e2aaaab
	v_fma_f32 v97, v94, v97, 0.5
	v_fma_f32 v97, v94, v97, 1.0
	v_mul_f32_e64 v97, v97, -v94
	v_fma_f32 v98, -v96, v96, 1.0
	v_cmp_lt_f32_e32 vcc, s94, v94
	v_max_f32_e32 v60, 0, v60
	v_sqrt_f32_e32 v60, v60
	v_cndmask_b32_e32 v94, v98, v97, vcc
	v_mul_f32_e32 v97, v128, v55
	v_mul_f32_e32 v98, 0x3fb8aa3b, v97
	v_add_f32_e32 v97, v97, v97
	v_fmamk_f32 v99, v97, 0x3ab60b61, v122
	v_exp_f32_e32 v98, v98
	v_fmaak_f32 v99, v97, v99, 0x3d2aaaab
	v_fmaak_f32 v99, v97, v99, 0x3e2aaaab
	v_fma_f32 v99, v97, v99, 0.5
	v_fma_f32 v99, v97, v99, 1.0
	v_max_f32_e32 v94, 0, v94
	v_mul_f32_e64 v99, v99, -v97
	v_fma_f32 v100, -v98, v98, 1.0
	v_cmp_lt_f32_e32 vcc, s94, v97
	v_sqrt_f32_e32 v94, v94
	v_mul_f32_e32 v60, v129, v60
	v_cndmask_b32_e32 v97, v100, v99, vcc
	v_max_f32_e32 v97, 0, v97
	v_sqrt_f32_e32 v97, v97
	v_mul_f32_e32 v64, v64, v94
	ds_write2st64_b32 v108, v93, v96 offset0:1 offset1:2
	ds_write2st64_b32 v108, v60, v64 offset0:132 offset1:133
	v_mul_f32_e32 v64, v67, v55
	v_mul_f32_e32 v60, v66, v97
	v_mul_f32_e32 v66, 0x3fb8aa3b, v64
	v_add_f32_e32 v64, v64, v64
	v_fmamk_f32 v67, v64, 0x3ab60b61, v122
	v_exp_f32_e32 v66, v66
	v_fmaak_f32 v67, v64, v67, 0x3d2aaaab
	v_fmaak_f32 v67, v64, v67, 0x3e2aaaab
	v_fma_f32 v67, v64, v67, 0.5
	v_fma_f32 v67, v64, v67, 1.0
	v_mul_f32_e64 v67, v67, -v64
	v_fma_f32 v93, -v66, v66, 1.0
	v_cmp_lt_f32_e32 vcc, s94, v64
	v_add_f32_e32 v46, 1.0, v46
	v_rcp_f32_e32 v46, v46
	v_cndmask_b32_e32 v64, v93, v67, vcc
	v_max_f32_e32 v64, 0, v64
	v_sqrt_f32_e32 v64, v64
	v_mul_f32_e32 v67, 0x3fb8aa3b, v65
	v_add_f32_e32 v65, v65, v65
	v_fmamk_f32 v93, v65, 0x3ab60b61, v122
	v_mul_f32_e32 v61, v61, v64
	ds_write2st64_b32 v108, v98, v66 offset0:3 offset1:16
	ds_write2st64_b32 v108, v60, v61 offset0:134 offset1:147
; __device__ __forceinline__ float sigmoid_(float x) { return __builtin_amdgcn_rcpf(1.f + __expf(-x)); }
; __device__ void lru_local_unit(const Params& p, unsigned char* smem, int unit) {
;     ...
; #pragma unroll
;     for (int ni = 0; ni < 4; ++ni) {
;       const int j = ni * 16 + l15;
;       const float ba = p.lru_ba[ch0 + j], bx = p.lru_bx[ch0 + j];
;       const float lam = p.lru_lambda[ch0 + j];
;       const float spl = -8.f * log1pf(__expf(-lam));
; #pragma unroll
;       for (int mi = 0; mi < 2; ++mi)
; #pragma unroll
;         for (int r = 0; r < 4; ++r) {
;           const int tt = wid * 32 + mi * 16 + q4 * 4 + r;
;           const float rg = sigmoid_(aa[mi][ni][r] + ba);
;           const float ig = sigmoid_(ax[mi][ni][r] + bx);
;           const float log_a = spl * rg;
;           const float av = __expf(log_a);
;           const float xl = R2[tt * 64 + j];
;           const float y2 = 2.f * log_a;
;           const float poly = -y2 * (1.f + y2 * (0.5f + y2 * (0.16666667f + y2 * (0.041666668f + y2 * (0.0083333338f + y2 * 0.0013888889f)))));
;           const float em = (y2 > -0.25f) ? poly : (1.f - av * av);
;           const float bv = __builtin_amdgcn_sqrtf(fmaxf(em, 0.f)) * (ig * xl);
;           R1[tt * 64 + j] = av;
;           R2[tt * 64 + j] = bv;
;         }
	v_mul_f32_e32 v60, v63, v55
	v_mul_f32_e32 v61, 0x3fb8aa3b, v60
	v_add_f32_e32 v60, v60, v60
	v_exp_f32_e32 v67, v67
	v_fmaak_f32 v93, v65, v93, 0x3d2aaaab
	v_exp_f32_e32 v63, v61
	v_fmamk_f32 v61, v60, 0x3ab60b61, v122
	v_fmaak_f32 v93, v65, v93, 0x3e2aaaab
	v_fmaak_f32 v61, v60, v61, 0x3d2aaaab
	v_fma_f32 v93, v65, v93, 0.5
	v_fmaak_f32 v61, v60, v61, 0x3e2aaaab
	v_fma_f32 v93, v65, v93, 1.0
	v_fma_f32 v61, v60, v61, 0.5
	v_mul_f32_e64 v93, v93, -v65
	v_fma_f32 v94, -v67, v67, 1.0
	v_cmp_lt_f32_e32 vcc, s94, v65
	v_fma_f32 v61, v60, v61, 1.0
	v_mul_f32_e64 v61, v61, -v60
	v_cndmask_b32_e32 v65, v94, v93, vcc
	v_fma_f32 v64, -v63, v63, 1.0
	v_cmp_lt_f32_e32 vcc, s94, v60
	v_max_f32_e32 v65, 0, v65
	v_mul_f32_e32 v55, 0x3fb8aa3b, v53
	v_cndmask_b32_e32 v60, v64, v61, vcc
	v_max_f32_e32 v60, 0, v60
	v_sqrt_f32_e32 v64, v60
	v_pk_add_f32 v[60:61], v[52:53], v[52:53]
	v_sqrt_f32_e32 v65, v65
	v_fmamk_f32 v53, v61, 0x3ab60b61, v122
	v_exp_f32_e32 v55, v55
	v_fmaak_f32 v53, v61, v53, 0x3d2aaaab
	v_fmaak_f32 v53, v61, v53, 0x3e2aaaab
	v_fma_f32 v53, v61, v53, 0.5
	v_fma_f32 v53, v61, v53, 1.0
	v_mul_f32_e32 v59, v59, v64
	v_mul_f32_e32 v62, v62, v65
	v_mul_f32_e64 v53, v53, -v61
	v_fma_f32 v65, -v55, v55, 1.0
	v_cmp_lt_f32_e32 vcc, s94, v61
	ds_write2st64_b32 v108, v67, v63 offset0:17 offset1:18
	ds_write2st64_b32 v108, v62, v59 offset0:148 offset1:149
	v_mul_f32_e32 v52, 0x3fb8aa3b, v52
	v_fmamk_f32 v59, v60, 0x3ab60b61, v122
	v_cndmask_b32_e32 v53, v65, v53, vcc
	v_exp_f32_e32 v52, v52
	v_fmaak_f32 v59, v60, v59, 0x3d2aaaab
	v_max_f32_e32 v53, 0, v53
	v_fmaak_f32 v59, v60, v59, 0x3e2aaaab
	v_sqrt_f32_e32 v53, v53
	v_fma_f32 v59, v60, v59, 0.5
	v_fma_f32 v59, v60, v59, 1.0
	v_mul_f32_e64 v59, v59, -v60
	v_fma_f32 v61, -v52, v52, 1.0
	v_cmp_lt_f32_e32 vcc, s94, v60
	v_mul_f32_e32 v53, v149, v53
	ds_write2st64_b32 v108, v55, v48 offset0:19 offset1:131
	ds_write_b32 v108, v53 offset:38400
	v_cndmask_b32_e32 v59, v61, v59, vcc
	v_max_f32_e32 v59, 0, v59
	v_add_f32_e32 v48, v49, v150
	v_sqrt_f32_e32 v59, v59
	v_mul_f32_e32 v48, 0xbfb8aa3b, v48
	v_exp_f32_e32 v48, v48
	ds_write2_b32 v108, v68, v52 offset1:16
	v_mul_f32_e32 v44, v44, v59
	ds_write_b32 v108, v44 offset:33600
	v_add_f32_e32 v44, 1.0, v48
	v_mul_f32_e32 v48, v45, v54
	v_rcp_f32_e32 v52, v44
	v_mul_f32_e32 v44, 0x3fb8aa3b, v48
	v_add_f32_e32 v48, v48, v48
	v_fmamk_f32 v49, v48, 0x3ab60b61, v122
	v_exp_f32_e32 v53, v44
	v_fmaak_f32 v49, v48, v49, 0x3d2aaaab
	v_fmaak_f32 v49, v48, v49, 0x3e2aaaab
	v_fma_f32 v49, v48, v49, 0.5
	v_fma_f32 v49, v48, v49, 1.0
	v_mul_f32_e64 v49, v49, -v48
	v_fma_f32 v55, -v53, v53, 1.0
	v_cmp_lt_f32_e32 vcc, s94, v48
	v_mul_f32_e32 v46, v46, v54
	ds_read2st64_b32 v[44:45], v109 offset0:132 offset1:133
	v_cndmask_b32_e32 v48, v55, v49, vcc
	v_add_f32_e32 v49, v50, v150
	v_mul_f32_e32 v49, 0xbfb8aa3b, v49
	v_exp_f32_e32 v49, v49
	v_max_f32_e32 v48, 0, v48
	v_sqrt_f32_e32 v50, v48
	s_waitcnt lgkmcnt(0)
	v_mul_f32_e32 v44, v44, v52
	v_add_f32_e32 v48, 1.0, v49
	v_rcp_f32_e32 v55, v48
	v_mul_f32_e32 v48, 0x3fb8aa3b, v46
	v_add_f32_e32 v46, v46, v46
	v_exp_f32_e32 v59, v48
	v_fmamk_f32 v48, v46, 0x3ab60b61, v122
	v_fmaak_f32 v48, v46, v48, 0x3d2aaaab
	v_fmaak_f32 v48, v46, v48, 0x3e2aaaab
	v_fma_f32 v48, v46, v48, 0.5
	v_fma_f32 v48, v46, v48, 1.0
	v_mul_f32_e64 v48, v48, -v46
	v_fma_f32 v49, -v59, v59, 1.0
	v_cmp_lt_f32_e32 vcc, s94, v46
	v_mul_f32_e32 v50, v44, v50
	v_mul_f32_e32 v44, v55, v45
	v_cndmask_b32_e32 v46, v49, v48, vcc
	v_max_f32_e32 v46, 0, v46
	v_sqrt_f32_e32 v46, v46
	v_add_f32_e32 v45, v51, v150
	v_add_f32_e32 v36, v36, v151
	v_mul_f32_e32 v45, 0xbfb8aa3b, v45
	v_mul_f32_e32 v46, v44, v46
	v_add_f32_e32 v44, v47, v151
	v_mul_f32_e32 v44, 0xbfb8aa3b, v44
	v_exp_f32_e32 v44, v44
	v_mul_f32_e32 v36, 0xbfb8aa3b, v36
	v_exp_f32_e32 v45, v45
	v_exp_f32_e32 v36, v36
	v_add_f32_e32 v44, 1.0, v44
	v_rcp_f32_e32 v44, v44
	v_add_f32_e32 v45, 1.0, v45
	v_add_f32_e32 v36, 1.0, v36
	ds_read2st64_b32 v[48:49], v109 offset0:148 offset1:149
	ds_read_b32 v60, v109 offset:38400
	v_mul_f32_e32 v51, v44, v54
	v_mul_f32_e32 v44, 0x3fb8aa3b, v51
	v_add_f32_e32 v51, v51, v51
	ds_write2st64_b32 v109, v53, v59 offset0:1 offset1:2
	v_rcp_f32_e32 v47, v45
	v_exp_f32_e32 v52, v44
	ds_read2st64_b32 v[44:45], v109 offset0:134 offset1:147
	v_fmamk_f32 v53, v51, 0x3ab60b61, v122
	v_rcp_f32_e32 v36, v36
	v_fmaak_f32 v53, v51, v53, 0x3d2aaaab
	v_fmaak_f32 v53, v51, v53, 0x3e2aaaab
	v_fma_f32 v53, v51, v53, 0.5
	v_fma_f32 v53, v51, v53, 1.0
	v_mul_f32_e32 v36, v36, v54
	v_mul_f32_e64 v53, v53, -v51
	v_fma_f32 v55, -v52, v52, 1.0
	v_cmp_lt_f32_e32 vcc, s94, v51
	s_waitcnt lgkmcnt(0)
; __device__ __forceinline__ float sigmoid_(float x) { return __builtin_amdgcn_rcpf(1.f + __expf(-x)); }
; __device__ void lru_local_unit(const Params& p, unsigned char* smem, int unit) {
;     ...
; #pragma unroll
;     for (int ni = 0; ni < 4; ++ni) {
;       const int j = ni * 16 + l15;
;       const float ba = p.lru_ba[ch0 + j], bx = p.lru_bx[ch0 + j];
;       const float lam = p.lru_lambda[ch0 + j];
;       const float spl = -8.f * log1pf(__expf(-lam));
; #pragma unroll
;       for (int mi = 0; mi < 2; ++mi)
; #pragma unroll
;         for (int r = 0; r < 4; ++r) {
;           const int tt = wid * 32 + mi * 16 + q4 * 4 + r;
;           const float rg = sigmoid_(aa[mi][ni][r] + ba);
;           const float ig = sigmoid_(ax[mi][ni][r] + bx);
;           const float log_a = spl * rg;
;           const float av = __expf(log_a);
;           const float xl = R2[tt * 64 + j];
;           const float y2 = 2.f * log_a;
;           const float poly = -y2 * (1.f + y2 * (0.5f + y2 * (0.16666667f + y2 * (0.041666668f + y2 * (0.0083333338f + y2 * 0.0013888889f)))));
;           const float em = (y2 > -0.25f) ? poly : (1.f - av * av);
;           const float bv = __builtin_amdgcn_sqrtf(fmaxf(em, 0.f)) * (ig * xl);
;           R1[tt * 64 + j] = av;
;           R2[tt * 64 + j] = bv;
;         }
	v_mul_f32_e32 v44, v47, v44
	v_mul_f32_e32 v47, 0x3fb8aa3b, v36
	v_add_f32_e32 v36, v36, v36
	v_cndmask_b32_e32 v51, v55, v53, vcc
	v_fmamk_f32 v53, v36, 0x3ab60b61, v122
	v_add_f32_e32 v37, v37, v151
	v_mul_f32_e32 v40, 0xbfb8aa3b, v40
	v_exp_f32_e32 v47, v47
	v_fmaak_f32 v53, v36, v53, 0x3d2aaaab
	v_mul_f32_e32 v37, 0xbfb8aa3b, v37
	v_exp_f32_e32 v40, v40
	v_fmaak_f32 v53, v36, v53, 0x3e2aaaab
	v_exp_f32_e32 v37, v37
	v_fma_f32 v53, v36, v53, 0.5
	v_fma_f32 v53, v36, v53, 1.0
	v_mul_f32_e64 v53, v53, -v36
	v_fma_f32 v55, -v47, v47, 1.0
	v_cmp_lt_f32_e32 vcc, s94, v36
	v_add_f32_e32 v40, 1.0, v40
	v_add_f32_e32 v37, 1.0, v37
	v_cndmask_b32_e32 v36, v55, v53, vcc
	v_max_f32_e32 v51, 0, v51
	v_rcp_f32_e32 v40, v40
	v_max_f32_e32 v36, 0, v36
	v_rcp_f32_e32 v37, v37
	v_sqrt_f32_e32 v51, v51
	v_sqrt_f32_e32 v36, v36
	v_mul_f32_e32 v40, v40, v45
	v_mul_f32_e32 v37, v37, v54
	v_mul_f32_e32 v44, v44, v51
	v_mul_f32_e32 v36, v40, v36
	v_add_f32_e32 v40, v41, v150
	v_mul_f32_e32 v41, 0x3fb8aa3b, v37
	v_add_f32_e32 v37, v37, v37
	ds_write2st64_b32 v109, v46, v44 offset0:133 offset1:134
	v_fmamk_f32 v44, v37, 0x3ab60b61, v122
	v_mul_f32_e32 v40, 0xbfb8aa3b, v40
	v_exp_f32_e32 v41, v41
	v_fmaak_f32 v44, v37, v44, 0x3d2aaaab
	v_add_f32_e32 v38, v38, v151
	v_exp_f32_e32 v40, v40
	v_fmaak_f32 v44, v37, v44, 0x3e2aaaab
	v_mul_f32_e32 v38, 0xbfb8aa3b, v38
	v_fma_f32 v44, v37, v44, 0.5
	v_exp_f32_e32 v38, v38
	v_fma_f32 v44, v37, v44, 1.0
	v_mul_f32_e64 v44, v44, -v37
	v_fma_f32 v45, -v41, v41, 1.0
	v_cmp_lt_f32_e32 vcc, s94, v37
	v_add_f32_e32 v40, 1.0, v40
	v_rcp_f32_e32 v40, v40
	v_cndmask_b32_e32 v37, v45, v44, vcc
	v_max_f32_e32 v37, 0, v37
	v_add_f32_e32 v38, 1.0, v38
	v_sqrt_f32_e32 v37, v37
	v_rcp_f32_e32 v38, v38
	v_mul_f32_e32 v40, v40, v48
	v_add_f32_e32 v42, v42, v150
	v_mul_f32_e32 v37, v40, v37
	v_mul_f32_e32 v38, v38, v54
	v_mul_f32_e32 v44, 0x3fb8aa3b, v38
	v_add_f32_e32 v38, v38, v38
	ds_write2st64_b32 v109, v36, v37 offset0:147 offset1:148
	v_add_f32_e32 v37, v39, v151
	v_fmamk_f32 v45, v38, 0x3ab60b61, v122
	v_mul_f32_e32 v37, 0xbfb8aa3b, v37
	v_mul_f32_e32 v42, 0xbfb8aa3b, v42
	v_exp_f32_e32 v44, v44
	v_fmaak_f32 v45, v38, v45, 0x3d2aaaab
	v_exp_f32_e32 v37, v37
	v_exp_f32_e32 v42, v42
	v_fmaak_f32 v45, v38, v45, 0x3e2aaaab
	v_fma_f32 v45, v38, v45, 0.5
	v_fma_f32 v45, v38, v45, 1.0
	v_mul_f32_e64 v45, v45, -v38
	v_fma_f32 v46, -v44, v44, 1.0
	v_cmp_lt_f32_e32 vcc, s94, v38
	v_add_f32_e32 v37, 1.0, v37
	v_add_f32_e32 v42, 1.0, v42
	v_cndmask_b32_e32 v38, v46, v45, vcc
	v_rcp_f32_e32 v37, v37
	v_rcp_f32_e32 v42, v42
	v_max_f32_e32 v38, 0, v38
	v_sqrt_f32_e32 v38, v38
	v_mul_f32_e32 v37, v37, v54
	v_mul_f32_e32 v36, v42, v49
	v_mul_f32_e32 v39, 0x3fb8aa3b, v37
	v_add_f32_e32 v37, v37, v37
	v_mul_f32_e32 v36, v36, v38
	v_add_f32_e32 v38, v43, v150
	v_fmamk_f32 v40, v37, 0x3ab60b61, v122
	v_mul_f32_e32 v38, 0xbfb8aa3b, v38
	v_exp_f32_e32 v39, v39
	v_fmaak_f32 v40, v37, v40, 0x3d2aaaab
	v_exp_f32_e32 v38, v38
	v_fmaak_f32 v40, v37, v40, 0x3e2aaaab
	v_fma_f32 v40, v37, v40, 0.5
	v_fma_f32 v40, v37, v40, 1.0
	ds_write2st64_b32 v109, v41, v44 offset0:17 offset1:18
	v_mul_f32_e64 v40, v40, -v37
	v_fma_f32 v41, -v39, v39, 1.0
	v_cmp_lt_f32_e32 vcc, s94, v37
	v_add_f32_e32 v38, 1.0, v38
	v_rcp_f32_e32 v38, v38
	v_cndmask_b32_e32 v37, v41, v40, vcc
	v_max_f32_e32 v37, 0, v37
	v_mul_f32_e32 v40, 0xbfb8aa3b, v133
	v_sqrt_f32_e32 v37, v37
	v_exp_f32_e32 v46, v40
	v_mul_f32_e32 v38, v38, v60
	ds_write2st64_b32 v109, v52, v47 offset0:3 offset1:16
	v_mul_f32_e32 v37, v38, v37
	v_add_f32_e32 v38, 1.0, v46
	ds_write2st64_b32 v109, v39, v50 offset0:19 offset1:132
	ds_write2st64_b32 v109, v36, v37 offset0:149 offset1:150
	v_add_f32_e32 v36, -1.0, v38
	v_sub_f32_e32 v37, v36, v38
	v_add_f32_e32 v37, 1.0, v37
	v_sub_f32_e32 v36, v46, v36
	v_add_f32_e32 v39, v36, v37
	v_frexp_mant_f32_e32 v40, v38
	v_cvt_f64_f32_e32 v[36:37], v38
	v_frexp_exp_i32_f64_e32 v36, v[36:37]
	v_cmp_gt_f32_e32 vcc, s90, v40
	v_add_f32_e32 v32, v32, v58
	v_mul_f32_e32 v32, 0xbfb8aa3b, v32
	v_subbrev_co_u32_e32 v44, vcc, 0, v36, vcc
	v_sub_u32_e32 v36, 0, v44
	v_ldexp_f32 v37, v38, v36
	v_add_f32_e32 v38, -1.0, v37
	v_add_f32_e32 v40, 1.0, v37
	v_ldexp_f32 v36, v39, v36
	v_add_f32_e32 v39, 1.0, v38
	v_add_f32_e32 v41, -1.0, v40
	v_sub_f32_e32 v39, v37, v39
	v_sub_f32_e32 v37, v37, v41
	v_add_f32_e32 v39, v36, v39
	v_add_f32_e32 v36, v36, v37
	v_add_f32_e32 v45, v40, v36
	v_rcp_f32_e32 v48, v45
	v_sub_f32_e32 v37, v45, v40
	v_sub_f32_e32 v47, v36, v37
	v_add_f32_e32 v37, v38, v39
	v_mul_f32_e32 v50, v37, v48
	v_sub_f32_e32 v36, v37, v38
	v_mul_f32_e32 v38, v45, v50
	v_fma_f32 v40, v50, v45, -v38
	v_fmac_f32_e32 v40, v50, v47
	v_sub_f32_e32 v49, v39, v36
	v_add_f32_e32 v36, v38, v40
	v_sub_f32_e32 v39, v37, v36
	v_pk_add_f32 v[42:43], v[36:37], v[38:39] neg_lo:[0,1] neg_hi:[0,1]
	v_mov_b32_e32 v41, v36
	v_pk_add_f32 v[36:37], v[42:43], v[40:41] neg_lo:[0,1] neg_hi:[0,1]
	v_exp_f32_e32 v32, v32
	v_add_f32_e32 v37, v49, v37
	v_add_f32_e32 v36, v36, v37
	v_add_f32_e32 v37, v39, v36
	v_mul_f32_e32 v49, v48, v37
	v_mul_f32_e32 v38, v45, v49
	v_fma_f32 v40, v49, v45, -v38
	v_fmac_f32_e32 v40, v49, v47
	v_sub_f32_e32 v39, v39, v37
	v_add_f32_e32 v45, v36, v39
	v_add_f32_e32 v36, v38, v40
	v_sub_f32_e32 v39, v37, v36
	v_pk_add_f32 v[42:43], v[36:37], v[38:39] neg_lo:[0,1] neg_hi:[0,1]
	v_mov_b32_e32 v41, v36
	v_pk_add_f32 v[36:37], v[42:43], v[40:41] neg_lo:[0,1] neg_hi:[0,1]
	v_add_f32_e32 v32, 1.0, v32
	v_add_f32_e32 v37, v45, v37
	v_add_f32_e32 v36, v36, v37
	v_add_f32_e32 v37, v50, v49
	v_add_f32_e32 v36, v39, v36
	v_sub_f32_e32 v38, v37, v50
	v_mul_f32_e32 v36, v48, v36
	v_sub_f32_e32 v38, v49, v38
; __device__ __forceinline__ float sigmoid_(float x) { return __builtin_amdgcn_rcpf(1.f + __expf(-x)); }
; __device__ void lru_local_unit(const Params& p, unsigned char* smem, int unit) {
;     ...
; #pragma unroll
;     for (int ni = 0; ni < 4; ++ni) {
;       const int j = ni * 16 + l15;
;       const float ba = p.lru_ba[ch0 + j], bx = p.lru_bx[ch0 + j];
;       const float lam = p.lru_lambda[ch0 + j];
;       const float spl = -8.f * log1pf(__expf(-lam));
; #pragma unroll
;       for (int mi = 0; mi < 2; ++mi)
; #pragma unroll
;         for (int r = 0; r < 4; ++r) {
;           const int tt = wid * 32 + mi * 16 + q4 * 4 + r;
;           const float rg = sigmoid_(aa[mi][ni][r] + ba);
;           const float ig = sigmoid_(ax[mi][ni][r] + bx);
;           const float log_a = spl * rg;
;           const float av = __expf(log_a);
;           const float xl = R2[tt * 64 + j];
;           const float y2 = 2.f * log_a;
;           const float poly = -y2 * (1.f + y2 * (0.5f + y2 * (0.16666667f + y2 * (0.041666668f + y2 * (0.0083333338f + y2 * 0.0013888889f)))));
;           const float em = (y2 > -0.25f) ? poly : (1.f - av * av);
;           const float bv = __builtin_amdgcn_sqrtf(fmaxf(em, 0.f)) * (ig * xl);
;           R1[tt * 64 + j] = av;
;           R2[tt * 64 + j] = bv;
;         }
	v_add_f32_e32 v38, v38, v36
	v_add_f32_e32 v39, v37, v38
	v_mul_f32_e32 v40, v39, v39
	v_fmamk_f32 v36, v40, 0x3e9b6dac, v121
	v_fmaak_f32 v93, v40, v36, 0x3f2aaada
	v_cvt_f32_i32_e32 v36, v44
	v_sub_f32_e32 v37, v39, v37
	v_sub_f32_e32 v37, v38, v37
	v_ldexp_f32 v42, v37, 1
	v_mul_f32_e32 v37, v39, v40
	v_ldexp_f32 v41, v39, 1
	v_pk_mul_f32 v[38:39], v[36:37], v[92:93]
	v_rcp_f32_e32 v32, v32
	v_fma_f32 v40, v36, s91, -v38
	v_fmac_f32_e32 v40, 0xb102e308, v36
	v_pk_add_f32 v[36:37], v[38:39], v[40:41]
	v_mfma_f32_16x16x32_bf16 v[24:27], v[160:163], v[176:179], v[152:155]
	v_sub_f32_e32 v41, v37, v41
	v_sub_f32_e32 v41, v39, v41
	v_add_f32_e32 v43, v42, v41
	v_mov_b32_e32 v42, v38
	v_pk_add_f32 v[44:45], v[36:37], v[38:39] neg_lo:[0,1] neg_hi:[0,1]
	v_pk_add_f32 v[48:49], v[36:37], v[42:43]
	v_mov_b32_e32 v41, v36
	v_mov_b32_e32 v45, v49
	v_pk_add_f32 v[38:39], v[40:41], v[44:45] neg_lo:[0,1] neg_hi:[0,1]
	v_pk_add_f32 v[40:41], v[40:41], v[44:45]
	v_mov_b32_e32 v42, v43
	v_pk_add_f32 v[44:45], v[40:41], v[36:37] op_sel:[1,0] op_sel_hi:[0,1] neg_lo:[0,1] neg_hi:[0,1]
	v_pk_add_f32 v[50:51], v[48:49], v[44:45] op_sel_hi:[1,0] neg_lo:[0,1] neg_hi:[0,1]
	v_mov_b32_e32 v40, v49
	v_pk_mov_b32 v[44:45], v[36:37], v[44:45] op_sel:[1,0]
	v_mov_b32_e32 v43, v36
	v_pk_add_f32 v[44:45], v[40:41], v[44:45] neg_lo:[0,1] neg_hi:[0,1]
	global_load_dword v40, v3, s[54:55] offset:192
	s_waitcnt vmcnt(2)
	v_add_f32_e32 v3, v29, v132
	v_mul_f32_e32 v3, 0xbfb8aa3b, v3
	v_add_f32_e32 v29, v33, v58
	v_exp_f32_e32 v3, v3
	v_mul_f32_e32 v29, 0xbfb8aa3b, v29
	ds_read2_b32 v[36:37], v123 offset0:224 offset1:240
	v_exp_f32_e32 v29, v29
	v_add_f32_e32 v3, 1.0, v3
	v_rcp_f32_e32 v47, v3
	v_pk_add_f32 v[42:43], v[42:43], v[44:45] neg_lo:[0,1] neg_hi:[0,1]
	v_add_f32_e32 v3, 1.0, v29
	v_add_f32_e32 v29, v30, v132
	s_waitcnt lgkmcnt(0)
	v_mul_f32_e32 v36, v36, v32
	ds_read2st64_b32 v[32:33], v110 offset0:132 offset1:133
	v_mul_f32_e32 v29, 0xbfb8aa3b, v29
	v_add_f32_e32 v30, v34, v58
	v_rcp_f32_e32 v3, v3
	v_exp_f32_e32 v29, v29
	v_mul_f32_e32 v30, 0xbfb8aa3b, v30
	v_exp_f32_e32 v34, v30
	s_waitcnt lgkmcnt(0)
	v_mul_f32_e32 v30, v32, v3
	v_add_f32_e32 v3, 1.0, v29
	v_add_f32_e32 v29, v31, v132
	v_rcp_f32_e32 v60, v3
	v_add_f32_e32 v3, 1.0, v34
	v_mul_f32_e32 v29, 0xbfb8aa3b, v29
	v_add_f32_e32 v31, v35, v58
	v_rcp_f32_e32 v3, v3
	v_exp_f32_e32 v29, v29
	v_mul_f32_e32 v31, 0xbfb8aa3b, v31
	v_exp_f32_e32 v32, v31
	v_mov_b32_e32 v50, v38
	v_mul_f32_e32 v31, v3, v33
	v_add_f32_e32 v3, 1.0, v29
	v_add_f32_e32 v20, v20, v132
	v_pk_add_f32 v[44:45], v[50:51], v[42:43]
	ds_read2st64_b32 v[48:49], v110 offset0:148 offset1:149
	ds_read_b32 v43, v110 offset:38400
	v_rcp_f32_e32 v61, v3
	v_add_f32_e32 v3, 1.0, v32
	ds_read2st64_b32 v[34:35], v110 offset0:134 offset1:147
	v_mul_f32_e32 v20, 0xbfb8aa3b, v20
	v_add_f32_e32 v24, v24, v58
	v_rcp_f32_e32 v3, v3
	v_exp_f32_e32 v20, v20
	v_mul_f32_e32 v24, 0xbfb8aa3b, v24
	v_exp_f32_e32 v24, v24
	s_waitcnt lgkmcnt(0)
	v_mul_f32_e32 v33, v3, v34
	v_add_f32_e32 v3, 1.0, v20
	v_add_f32_e32 v20, v21, v132
	v_rcp_f32_e32 v32, v3
	v_add_f32_e32 v3, 1.0, v24
	v_mul_f32_e32 v20, 0xbfb8aa3b, v20
	v_rcp_f32_e32 v3, v3
	v_exp_f32_e32 v20, v20
	v_add_f32_e32 v21, v25, v58
	v_mul_f32_e32 v21, 0xbfb8aa3b, v21
	v_exp_f32_e32 v21, v21
	v_mul_f32_e32 v24, v3, v35
	v_add_f32_e32 v3, 1.0, v20
	v_add_f32_e32 v20, v26, v58
	v_mul_f32_e32 v20, 0xbfb8aa3b, v20
	v_exp_f32_e32 v20, v20
	v_rcp_f32_e32 v29, v3
	v_add_f32_e32 v3, 1.0, v21
	v_add_f32_e32 v21, v22, v132
	v_mul_f32_e32 v21, 0xbfb8aa3b, v21
	v_rcp_f32_e32 v3, v3
	v_exp_f32_e32 v21, v21
	v_add_f32_e32 v20, 1.0, v20
	v_rcp_f32_e32 v20, v20
	v_mul_f32_e32 v26, v3, v48
	v_add_f32_e32 v3, 1.0, v21
	v_rcp_f32_e32 v25, v3
	v_mul_f32_e32 v3, v20, v49
	v_add_f32_e32 v20, v27, v58
	v_mul_f32_e32 v20, 0xbfb8aa3b, v20
	v_exp_f32_e32 v20, v20
	v_add_f32_e32 v21, v23, v132
	v_mul_f32_e32 v21, 0xbfb8aa3b, v21
	s_waitcnt vmcnt(0)
	v_mul_f32_e32 v22, 0xbfb8aa3b, v40
	v_add_f32_e32 v20, 1.0, v20
	v_exp_f32_e32 v22, v22
	v_exp_f32_e32 v21, v21
	v_rcp_f32_e32 v20, v20
	v_mov_b32_e32 v39, v41
	v_add_f32_e32 v34, 1.0, v22
	v_add_f32_e32 v21, 1.0, v21
	v_mul_f32_e32 v27, v20, v43
	v_add_f32_e32 v20, -1.0, v34
	v_rcp_f32_e32 v23, v21
	v_sub_f32_e32 v21, v20, v34
	v_add_f32_e32 v21, 1.0, v21
	v_sub_f32_e32 v20, v22, v20
	v_add_f32_e32 v35, v20, v21
	v_frexp_mant_f32_e32 v40, v34
	v_cvt_f64_f32_e32 v[20:21], v34
	v_frexp_exp_i32_f64_e32 v20, v[20:21]
	v_cmp_gt_f32_e32 vcc, s90, v40
	v_add_f32_e32 v28, v28, v132
	v_mul_f32_e32 v28, 0xbfb8aa3b, v28
	v_subbrev_co_u32_e32 v40, vcc, 0, v20, vcc
	v_sub_u32_e32 v20, 0, v40
	v_ldexp_f32 v21, v34, v20
	v_add_f32_e32 v34, -1.0, v21
	v_add_f32_e32 v43, 1.0, v21
	v_ldexp_f32 v20, v35, v20
	v_add_f32_e32 v35, 1.0, v34
	v_add_f32_e32 v48, -1.0, v43
	v_sub_f32_e32 v35, v21, v35
	v_sub_f32_e32 v21, v21, v48
	v_add_f32_e32 v35, v20, v35
	v_add_f32_e32 v20, v20, v21
	v_add_f32_e32 v52, v43, v20
	v_rcp_f32_e32 v53, v52
	v_sub_f32_e32 v21, v52, v43
	v_sub_f32_e32 v43, v20, v21
	v_add_f32_e32 v21, v34, v35
	v_mul_f32_e32 v55, v21, v53
	v_sub_f32_e32 v20, v21, v34
	v_mul_f32_e32 v34, v52, v55
	v_fma_f32 v48, v55, v52, -v34
	v_fmac_f32_e32 v48, v55, v43
	v_sub_f32_e32 v54, v35, v20
	v_add_f32_e32 v20, v34, v48
	v_sub_f32_e32 v35, v21, v20
	v_pk_add_f32 v[50:51], v[20:21], v[34:35] neg_lo:[0,1] neg_hi:[0,1]
	v_mov_b32_e32 v49, v20
	v_pk_add_f32 v[20:21], v[50:51], v[48:49] neg_lo:[0,1] neg_hi:[0,1]
	v_cmp_neq_f32_e32 vcc, s92, v22
	v_add_f32_e32 v21, v54, v21
	v_add_f32_e32 v20, v20, v21
	v_add_f32_e32 v21, v35, v20
	v_mul_f32_e32 v54, v53, v21
	v_mul_f32_e32 v34, v52, v54
	v_fma_f32 v48, v54, v52, -v34
; __device__ __forceinline__ float sigmoid_(float x) { return __builtin_amdgcn_rcpf(1.f + __expf(-x)); }
; __device__ void lru_local_unit(const Params& p, unsigned char* smem, int unit) {
;     ...
; #pragma unroll
;     for (int ni = 0; ni < 4; ++ni) {
;       const int j = ni * 16 + l15;
;       const float ba = p.lru_ba[ch0 + j], bx = p.lru_bx[ch0 + j];
;       const float lam = p.lru_lambda[ch0 + j];
;       const float spl = -8.f * log1pf(__expf(-lam));
; #pragma unroll
;       for (int mi = 0; mi < 2; ++mi)
; #pragma unroll
;         for (int r = 0; r < 4; ++r) {
;           const int tt = wid * 32 + mi * 16 + q4 * 4 + r;
;           const float rg = sigmoid_(aa[mi][ni][r] + ba);
;           const float ig = sigmoid_(ax[mi][ni][r] + bx);
;           const float log_a = spl * rg;
;           const float av = __expf(log_a);
;           const float xl = R2[tt * 64 + j];
;           const float y2 = 2.f * log_a;
;           const float poly = -y2 * (1.f + y2 * (0.5f + y2 * (0.16666667f + y2 * (0.041666668f + y2 * (0.0083333338f + y2 * 0.0013888889f)))));
;           const float em = (y2 > -0.25f) ? poly : (1.f - av * av);
;           const float bv = __builtin_amdgcn_sqrtf(fmaxf(em, 0.f)) * (ig * xl);
;           R1[tt * 64 + j] = av;
;           R2[tt * 64 + j] = bv;
;         }
	v_fmac_f32_e32 v48, v54, v43
	v_sub_f32_e32 v35, v35, v21
	v_add_f32_e32 v43, v20, v35
	v_add_f32_e32 v20, v34, v48
	v_sub_f32_e32 v35, v21, v20
	v_pk_add_f32 v[50:51], v[20:21], v[34:35] neg_lo:[0,1] neg_hi:[0,1]
	v_mov_b32_e32 v49, v20
	v_pk_add_f32 v[20:21], v[50:51], v[48:49] neg_lo:[0,1] neg_hi:[0,1]
	v_exp_f32_e32 v28, v28
	v_add_f32_e32 v21, v43, v21
	v_add_f32_e32 v20, v20, v21
	v_add_f32_e32 v21, v55, v54
	v_add_f32_e32 v20, v35, v20
	v_sub_f32_e32 v34, v21, v55
	v_mul_f32_e32 v20, v53, v20
	v_sub_f32_e32 v34, v54, v34
	v_add_f32_e32 v34, v34, v20
	v_add_f32_e32 v43, v21, v34
	v_mul_f32_e32 v48, v43, v43
	v_fmamk_f32 v20, v48, 0x3e9b6dac, v121
	v_fmaak_f32 v93, v48, v20, 0x3f2aaada
	v_cvt_f32_i32_e32 v20, v40
	v_sub_f32_e32 v21, v43, v21
	v_sub_f32_e32 v21, v34, v21
	v_ldexp_f32 v40, v21, 1
	v_mul_f32_e32 v21, v43, v48
	v_pk_mul_f32 v[48:49], v[20:21], v[92:93]
	v_ldexp_f32 v35, v43, 1
	v_fma_f32 v34, v20, s91, -v48
	v_fmac_f32_e32 v34, 0xb102e308, v20
	v_pk_add_f32 v[20:21], v[48:49], v[34:35]
	v_mov_b32_e32 v50, v48
	v_sub_f32_e32 v35, v21, v35
	v_sub_f32_e32 v35, v49, v35
	v_add_f32_e32 v51, v40, v35
	v_pk_add_f32 v[48:49], v[20:21], v[48:49] neg_lo:[0,1] neg_hi:[0,1]
	v_pk_add_f32 v[52:53], v[20:21], v[50:51]
	v_mov_b32_e32 v35, v20
	v_mov_b32_e32 v49, v53
	v_pk_add_f32 v[54:55], v[34:35], v[48:49] neg_lo:[0,1] neg_hi:[0,1]
	v_pk_add_f32 v[34:35], v[34:35], v[48:49]
	v_mov_b32_e32 v50, v51
	v_pk_add_f32 v[48:49], v[34:35], v[20:21] op_sel:[1,0] op_sel_hi:[0,1] neg_lo:[0,1] neg_hi:[0,1]
	v_pk_add_f32 v[58:59], v[52:53], v[48:49] op_sel_hi:[1,0] neg_lo:[0,1] neg_hi:[0,1]
	v_mov_b32_e32 v34, v53
	v_pk_mov_b32 v[48:49], v[20:21], v[48:49] op_sel:[1,0]
	v_mov_b32_e32 v51, v20
	v_pk_add_f32 v[48:49], v[34:35], v[48:49] neg_lo:[0,1] neg_hi:[0,1]
	v_mov_b32_e32 v58, v54
	v_pk_add_f32 v[20:21], v[50:51], v[48:49] neg_lo:[0,1] neg_hi:[0,1]
	v_mov_b32_e32 v51, v44
	v_pk_add_f32 v[48:49], v[58:59], v[20:21]
	v_mov_b32_e32 v53, v45
	v_mov_b32_e32 v50, v48
	v_mov_b32_e32 v52, v49
	v_pk_add_f32 v[52:53], v[50:51], v[52:53]
	v_mov_b32_e32 v40, v35
	v_mov_b32_e32 v55, v35
	v_pk_add_f32 v[34:35], v[40:41], v[52:53]
	v_mov_b32_e32 v43, v53
	v_mov_b32_e32 v45, v35
	v_mov_b32_e32 v49, v34
	v_pk_add_f32 v[40:41], v[44:45], v[38:39] neg_lo:[0,1] neg_hi:[0,1]
	v_pk_add_f32 v[44:45], v[48:49], v[54:55] neg_lo:[0,1] neg_hi:[0,1]
	v_mov_b32_e32 v49, v40
	v_mov_b32_e32 v48, v44
	v_mov_b32_e32 v21, v52
	v_pk_add_f32 v[42:43], v[42:43], v[40:41] neg_lo:[0,1] neg_hi:[0,1]
	v_pk_add_f32 v[40:41], v[50:51], v[48:49] neg_lo:[0,1] neg_hi:[0,1]
	v_mov_b32_e32 v55, v38
	v_pk_add_f32 v[20:21], v[20:21], v[44:45] neg_lo:[0,1] neg_hi:[0,1]
	v_pk_add_f32 v[38:39], v[54:55], v[40:41] neg_lo:[0,1] neg_hi:[0,1]
	v_mov_b32_e32 v40, v20
	v_mov_b32_e32 v41, v42
	v_pk_add_f32 v[38:39], v[40:41], v[38:39]
	v_mov_b32_e32 v42, v21
	v_pk_add_f32 v[20:21], v[38:39], v[42:43]
	v_add_f32_e32 v28, 1.0, v28
	v_pk_add_f32 v[20:21], v[34:35], v[20:21]
	v_rcp_f32_e32 v28, v28
	v_cndmask_b32_e32 v20, v124, v20, vcc
	v_cmp_neq_f32_e32 vcc, s92, v46
	v_mfma_f32_16x16x32_bf16 v[16:19], v[180:183], v[188:191], v[16:19]
	v_add_f32_e32 v12, v12, v57
	v_cndmask_b32_e32 v21, v124, v21, vcc
	v_cmp_ngt_f32_e32 vcc, -1.0, v46
	v_mul_f32_e32 v12, 0xbfb8aa3b, v12
	v_exp_f32_e32 v12, v12
	v_cndmask_b32_e32 v21, v125, v21, vcc
	v_cmp_ngt_f32_e32 vcc, -1.0, v22
	s_nop 0
	v_add_f32_e32 v16, v16, v56
	v_mul_f32_e32 v16, 0xbfb8aa3b, v16
	v_cndmask_b32_e32 v20, v125, v20, vcc
	v_cmp_neq_f32_e32 vcc, -1.0, v22
	v_exp_f32_e32 v16, v16
	v_add_f32_e32 v12, 1.0, v12
	v_cndmask_b32_e32 v20, v126, v20, vcc
	v_cmp_neq_f32_e32 vcc, -1.0, v46
	v_add_f32_e32 v4, v4, v57
	v_mul_f32_e32 v4, 0xbfb8aa3b, v4
	v_cndmask_b32_e32 v21, v126, v21, vcc
	v_cmp_lt_f32_e64 vcc, |v46|, s93
	v_exp_f32_e32 v4, v4
	v_mfma_f32_16x16x32_bf16 v[8:11], v[160:163], v[188:191], v[184:187]
	v_cndmask_b32_e32 v21, v21, v46, vcc
	v_cmp_lt_f32_e64 vcc, |v22|, s93
	v_add_f32_e32 v4, 1.0, v4
	v_add_f32_e32 v5, v5, v57
	v_cndmask_b32_e32 v20, v20, v22, vcc
	v_pk_mul_f32 v[20:21], v[20:21], s[38:39] op_sel_hi:[1,0]
	s_nop 1
	v_add_f32_e32 v8, v8, v56
	v_mul_f32_e32 v22, v28, v21
	v_mul_f32_e32 v28, 0x3fb8aa3b, v22
	v_add_f32_e32 v22, v22, v22
	v_fmamk_f32 v34, v22, 0x3ab60b61, v122
	v_exp_f32_e32 v28, v28
	v_fmaak_f32 v34, v22, v34, 0x3d2aaaab
	v_fmaak_f32 v34, v22, v34, 0x3e2aaaab
	v_fma_f32 v34, v22, v34, 0.5
	v_fma_f32 v34, v22, v34, 1.0
	v_mul_f32_e64 v34, v34, -v22
	v_fma_f32 v35, -v28, v28, 1.0
	v_cmp_lt_f32_e32 vcc, s94, v22
	v_mul_f32_e32 v29, v29, v21
	v_rcp_f32_e32 v4, v4
	v_cndmask_b32_e32 v22, v35, v34, vcc
	v_max_f32_e32 v22, 0, v22
	v_sqrt_f32_e32 v34, v22
	v_rcp_f32_e32 v22, v12
	v_add_f32_e32 v12, 1.0, v16
	v_rcp_f32_e32 v12, v12
	v_mul_f32_e32 v16, v36, v34
	ds_write_b32 v108, v28 offset:128
	ds_write_b32 v108, v16 offset:33664
	v_mul_f32_e32 v16, v47, v21
	v_mul_f32_e32 v28, 0x3fb8aa3b, v16
	v_add_f32_e32 v16, v16, v16
	v_fmamk_f32 v34, v16, 0x3ab60b61, v122
	v_exp_f32_e32 v28, v28
	v_fmaak_f32 v34, v16, v34, 0x3d2aaaab
	v_fmaak_f32 v34, v16, v34, 0x3e2aaaab
	v_fma_f32 v34, v16, v34, 0.5
	v_fma_f32 v34, v16, v34, 1.0
	v_mul_f32_e64 v34, v34, -v16
	v_fma_f32 v35, -v28, v28, 1.0
	v_cmp_lt_f32_e32 vcc, s94, v16
	v_pk_mul_f32 v[22:23], v[22:23], v[20:21]
	v_mul_f32_e32 v5, 0xbfb8aa3b, v5
	v_cndmask_b32_e32 v16, v35, v34, vcc
	v_mul_f32_e32 v34, v60, v21
	v_mul_f32_e32 v35, 0x3fb8aa3b, v34
	v_add_f32_e32 v34, v34, v34
	v_fmamk_f32 v36, v34, 0x3ab60b61, v122
	v_exp_f32_e32 v35, v35
	v_fmaak_f32 v36, v34, v36, 0x3d2aaaab
	v_fmaak_f32 v36, v34, v36, 0x3e2aaaab
	v_fma_f32 v36, v34, v36, 0.5
	v_fma_f32 v36, v34, v36, 1.0
; __device__ __forceinline__ float sigmoid_(float x) { return __builtin_amdgcn_rcpf(1.f + __expf(-x)); }
; __device__ void lru_local_unit(const Params& p, unsigned char* smem, int unit) {
;     ...
; #pragma unroll
;     for (int ni = 0; ni < 4; ++ni) {
;       const int j = ni * 16 + l15;
;       const float ba = p.lru_ba[ch0 + j], bx = p.lru_bx[ch0 + j];
;       const float lam = p.lru_lambda[ch0 + j];
;       const float spl = -8.f * log1pf(__expf(-lam));
; #pragma unroll
;       for (int mi = 0; mi < 2; ++mi)
; #pragma unroll
;         for (int r = 0; r < 4; ++r) {
;           const int tt = wid * 32 + mi * 16 + q4 * 4 + r;
;           const float rg = sigmoid_(aa[mi][ni][r] + ba);
;           const float ig = sigmoid_(ax[mi][ni][r] + bx);
;           const float log_a = spl * rg;
;           const float av = __expf(log_a);
;           const float xl = R2[tt * 64 + j];
;           const float y2 = 2.f * log_a;
;           const float poly = -y2 * (1.f + y2 * (0.5f + y2 * (0.16666667f + y2 * (0.041666668f + y2 * (0.0083333338f + y2 * 0.0013888889f)))));
;           const float em = (y2 > -0.25f) ? poly : (1.f - av * av);
;           const float bv = __builtin_amdgcn_sqrtf(fmaxf(em, 0.f)) * (ig * xl);
;           R1[tt * 64 + j] = av;
;           R2[tt * 64 + j] = bv;
;         }
	v_mul_f32_e64 v36, v36, -v34
	v_fma_f32 v38, -v35, v35, 1.0
	v_cmp_lt_f32_e32 vcc, s94, v34
	v_max_f32_e32 v16, 0, v16
	v_sqrt_f32_e32 v16, v16
	v_cndmask_b32_e32 v34, v38, v36, vcc
	v_mul_f32_e32 v36, v61, v21
	v_mul_f32_e32 v38, 0x3fb8aa3b, v36
	v_add_f32_e32 v36, v36, v36
	v_fmamk_f32 v39, v36, 0x3ab60b61, v122
	v_exp_f32_e32 v38, v38
	v_fmaak_f32 v39, v36, v39, 0x3d2aaaab
	v_fmaak_f32 v39, v36, v39, 0x3e2aaaab
	v_fma_f32 v39, v36, v39, 0.5
	v_fma_f32 v39, v36, v39, 1.0
	v_max_f32_e32 v34, 0, v34
	v_mul_f32_e64 v39, v39, -v36
	v_fma_f32 v40, -v38, v38, 1.0
	v_cmp_lt_f32_e32 vcc, s94, v36
	v_sqrt_f32_e32 v34, v34
	v_mul_f32_e32 v16, v30, v16
	v_cndmask_b32_e32 v36, v40, v39, vcc
	v_max_f32_e32 v36, 0, v36
	v_sqrt_f32_e32 v36, v36
	v_mul_f32_e32 v30, v31, v34
	v_mul_f32_e32 v31, v32, v21
	v_mul_f32_e32 v32, 0x3fb8aa3b, v31
	v_add_f32_e32 v31, v31, v31
	ds_write2st64_b32 v110, v28, v35 offset0:1 offset1:2
	v_mul_f32_e32 v28, v33, v36
	v_fmamk_f32 v33, v31, 0x3ab60b61, v122
	v_exp_f32_e32 v32, v32
	v_fmaak_f32 v33, v31, v33, 0x3d2aaaab
	v_fmaak_f32 v33, v31, v33, 0x3e2aaaab
	v_fma_f32 v33, v31, v33, 0.5
	v_fma_f32 v33, v31, v33, 1.0
	v_mul_f32_e64 v33, v33, -v31
	v_fma_f32 v34, -v32, v32, 1.0
	v_cmp_lt_f32_e32 vcc, s94, v31
	ds_write2st64_b32 v110, v30, v28 offset0:133 offset1:134
	ds_write2st64_b32 v110, v38, v32 offset0:3 offset1:16
	v_cndmask_b32_e32 v31, v34, v33, vcc
	v_mul_f32_e32 v33, 0x3fb8aa3b, v29
	v_add_f32_e32 v29, v29, v29
	v_fmamk_f32 v34, v29, 0x3ab60b61, v122
	v_exp_f32_e32 v33, v33
	v_fmaak_f32 v34, v29, v34, 0x3d2aaaab
	v_fmaak_f32 v34, v29, v34, 0x3e2aaaab
	v_fma_f32 v34, v29, v34, 0.5
	v_fma_f32 v34, v29, v34, 1.0
	v_max_f32_e32 v31, 0, v31
	v_mul_f32_e64 v34, v34, -v29
	v_fma_f32 v35, -v33, v33, 1.0
	v_cmp_lt_f32_e32 vcc, s94, v29
	v_sqrt_f32_e32 v31, v31
	v_mul_f32_e32 v8, 0xbfb8aa3b, v8
	v_cndmask_b32_e32 v29, v35, v34, vcc
	v_max_f32_e32 v29, 0, v29
	v_sqrt_f32_e32 v29, v29
	v_mul_f32_e32 v28, v24, v31
	v_mul_f32_e32 v24, v25, v21
	v_mul_f32_e32 v25, 0x3fb8aa3b, v24
	v_add_f32_e32 v24, v24, v24
	v_mul_f32_e32 v26, v26, v29
	v_exp_f32_e32 v29, v25
	v_fmamk_f32 v25, v24, 0x3ab60b61, v122
	v_fmaak_f32 v25, v24, v25, 0x3d2aaaab
	v_fmaak_f32 v25, v24, v25, 0x3e2aaaab
	v_fma_f32 v25, v24, v25, 0.5
	v_fma_f32 v25, v24, v25, 1.0
	v_mul_f32_e64 v25, v25, -v24
	v_fma_f32 v30, -v29, v29, 1.0
	v_cmp_lt_f32_e32 vcc, s94, v24
	v_mul_f32_e32 v21, 0x3fb8aa3b, v23
	v_exp_f32_e32 v21, v21
	v_cndmask_b32_e32 v24, v30, v25, vcc
	v_max_f32_e32 v24, 0, v24
	v_sqrt_f32_e32 v30, v24
	v_pk_add_f32 v[24:25], v[22:23], v[22:23]
	v_fma_f32 v31, -v21, v21, 1.0
	v_fmamk_f32 v23, v25, 0x3ab60b61, v122
	v_fmaak_f32 v23, v25, v23, 0x3d2aaaab
	v_fmaak_f32 v23, v25, v23, 0x3e2aaaab
	v_fma_f32 v23, v25, v23, 0.5
	v_fma_f32 v23, v25, v23, 1.0
	v_mul_f32_e64 v23, v23, -v25
	v_cmp_lt_f32_e32 vcc, s94, v25
	v_mul_f32_e32 v3, v3, v30
	v_mul_f32_e32 v22, 0x3fb8aa3b, v22
	v_cndmask_b32_e32 v23, v31, v23, vcc
	v_max_f32_e32 v23, 0, v23
	v_sqrt_f32_e32 v23, v23
	v_fmamk_f32 v25, v24, 0x3ab60b61, v122
	ds_write2st64_b32 v110, v28, v26 offset0:147 offset1:148
	ds_write2st64_b32 v110, v33, v29 offset0:17 offset1:18
	v_mul_f32_e32 v23, v27, v23
	v_exp_f32_e32 v22, v22
	v_fmaak_f32 v25, v24, v25, 0x3d2aaaab
	ds_write2st64_b32 v110, v21, v16 offset0:19 offset1:132
	ds_write2st64_b32 v110, v3, v23 offset0:149 offset1:150
	v_mul_f32_e32 v3, v37, v12
	v_add_f32_e32 v12, v13, v57
	v_fmaak_f32 v25, v24, v25, 0x3e2aaaab
	v_mul_f32_e32 v12, 0xbfb8aa3b, v12
	v_fma_f32 v25, v24, v25, 0.5
	v_exp_f32_e32 v12, v12
	v_fma_f32 v25, v24, v25, 1.0
	v_mul_f32_e64 v25, v25, -v24
	v_fma_f32 v26, -v22, v22, 1.0
	v_cmp_lt_f32_e32 vcc, s94, v24
	v_add_f32_e32 v12, 1.0, v12
	v_add_f32_e32 v13, v17, v56
	v_cndmask_b32_e32 v24, v26, v25, vcc
	v_max_f32_e32 v24, 0, v24
	v_sqrt_f32_e32 v24, v24
	v_rcp_f32_e32 v12, v12
	v_mul_f32_e32 v13, 0xbfb8aa3b, v13
	v_exp_f32_e32 v13, v13
	v_mul_f32_e32 v3, v3, v24
	v_mul_f32_e32 v16, v12, v20
	ds_write_b32 v108, v3 offset:33728
	v_mul_f32_e32 v12, 0x3fb8aa3b, v16
	v_add_f32_e32 v3, 1.0, v13
	v_exp_f32_e32 v21, v12
	ds_read2st64_b32 v[12:13], v111 offset0:132 offset1:133
	v_rcp_f32_e32 v3, v3
	v_add_f32_e32 v16, v16, v16
	v_fmamk_f32 v17, v16, 0x3ab60b61, v122
	v_fmaak_f32 v17, v16, v17, 0x3d2aaaab
	s_waitcnt lgkmcnt(0)
; __device__ __forceinline__ float sigmoid_(float x) { return __builtin_amdgcn_rcpf(1.f + __expf(-x)); }
; __device__ void lru_local_unit(const Params& p, unsigned char* smem, int unit) {
;     ...
; #pragma unroll
;     for (int ni = 0; ni < 4; ++ni) {
;       const int j = ni * 16 + l15;
;       const float ba = p.lru_ba[ch0 + j], bx = p.lru_bx[ch0 + j];
;       const float lam = p.lru_lambda[ch0 + j];
;       const float spl = -8.f * log1pf(__expf(-lam));
; #pragma unroll
;       for (int mi = 0; mi < 2; ++mi)
; #pragma unroll
;         for (int r = 0; r < 4; ++r) {
;           const int tt = wid * 32 + mi * 16 + q4 * 4 + r;
;           const float rg = sigmoid_(aa[mi][ni][r] + ba);
;           const float ig = sigmoid_(ax[mi][ni][r] + bx);
;           const float log_a = spl * rg;
;           const float av = __expf(log_a);
;           const float xl = R2[tt * 64 + j];
;           const float y2 = 2.f * log_a;
;           const float poly = -y2 * (1.f + y2 * (0.5f + y2 * (0.16666667f + y2 * (0.041666668f + y2 * (0.0083333338f + y2 * 0.0013888889f)))));
;           const float em = (y2 > -0.25f) ? poly : (1.f - av * av);
;           const float bv = __builtin_amdgcn_sqrtf(fmaxf(em, 0.f)) * (ig * xl);
;           R1[tt * 64 + j] = av;
;           R2[tt * 64 + j] = bv;
;         }
;     }
;   }
;   __syncthreads();
;   {
;     const int j = tid & 63, seg = tid >> 6;
;     float h = 0.f, Ac = 1.f;
	v_mul_f32_e32 v3, v12, v3
	v_add_f32_e32 v12, v14, v57
	v_mul_f32_e32 v12, 0xbfb8aa3b, v12
	v_exp_f32_e32 v12, v12
	v_fmaak_f32 v17, v16, v17, 0x3e2aaaab
	v_fma_f32 v17, v16, v17, 0.5
	v_fma_f32 v17, v16, v17, 1.0
	ds_write_b32 v108, v22 offset:192
	v_mul_f32_e64 v17, v17, -v16
	v_fma_f32 v22, -v21, v21, 1.0
	v_cmp_lt_f32_e32 vcc, s94, v16
	v_add_f32_e32 v12, 1.0, v12
	v_rcp_f32_e32 v12, v12
	v_cndmask_b32_e32 v16, v22, v17, vcc
	v_max_f32_e32 v16, 0, v16
	v_sqrt_f32_e32 v22, v16
	v_mul_f32_e32 v12, v12, v20
	v_add_f32_e32 v14, v18, v56
	v_mul_f32_e32 v18, 0x3fb8aa3b, v12
	v_add_f32_e32 v12, v12, v12
	v_mul_f32_e32 v3, v3, v22
	v_fmamk_f32 v22, v12, 0x3ab60b61, v122
	v_exp_f32_e32 v18, v18
	v_fmaak_f32 v22, v12, v22, 0x3d2aaaab
	v_fmaak_f32 v22, v12, v22, 0x3e2aaaab
	v_fma_f32 v22, v12, v22, 0.5
	v_fma_f32 v22, v12, v22, 1.0
	v_mul_f32_e64 v22, v22, -v12
	v_fma_f32 v24, -v18, v18, 1.0
	v_cmp_lt_f32_e32 vcc, s94, v12
	v_mul_f32_e32 v14, 0xbfb8aa3b, v14
	v_exp_f32_e32 v14, v14
	v_cndmask_b32_e32 v12, v24, v22, vcc
	v_max_f32_e32 v12, 0, v12
	v_sqrt_f32_e32 v22, v12
	v_add_f32_e32 v12, v15, v57
	v_mul_f32_e32 v12, 0xbfb8aa3b, v12
	v_exp_f32_e32 v12, v12
	v_add_f32_e32 v15, v19, v56
	v_add_f32_e32 v14, 1.0, v14
	v_mul_f32_e32 v15, 0xbfb8aa3b, v15
	v_add_f32_e32 v12, 1.0, v12
	v_rcp_f32_e32 v12, v12
	v_rcp_f32_e32 v14, v14
	v_exp_f32_e32 v15, v15
	ds_read2st64_b32 v[16:17], v111 offset0:148 offset1:149
	ds_read_b32 v23, v111 offset:38400
	v_mul_f32_e32 v19, v12, v20
	v_mul_f32_e32 v12, 0x3fb8aa3b, v19
	v_add_f32_e32 v19, v19, v19
	v_fmamk_f32 v25, v19, 0x3ab60b61, v122
	v_exp_f32_e32 v24, v12
	v_fmaak_f32 v25, v19, v25, 0x3d2aaaab
	v_fmaak_f32 v25, v19, v25, 0x3e2aaaab
	v_fma_f32 v25, v19, v25, 0.5
	v_fma_f32 v25, v19, v25, 1.0
	v_mul_f32_e32 v14, v14, v13
	v_add_f32_e32 v13, 1.0, v15
	v_mul_f32_e64 v25, v25, -v19
	v_fma_f32 v26, -v24, v24, 1.0
	v_cmp_lt_f32_e32 vcc, s94, v19
	v_rcp_f32_e32 v15, v13
	ds_read2st64_b32 v[12:13], v111 offset0:134 offset1:147
	v_cndmask_b32_e32 v19, v26, v25, vcc
	v_max_f32_e32 v19, 0, v19
	v_sqrt_f32_e32 v19, v19
	v_exp_f32_e32 v5, v5
	v_exp_f32_e32 v8, v8
	s_waitcnt lgkmcnt(0)
	v_mul_f32_e32 v12, v15, v12
	v_mul_f32_e32 v14, v14, v22
	v_mul_f32_e32 v12, v12, v19
	v_mul_f32_e32 v4, v4, v20
	ds_write2st64_b32 v111, v14, v12 offset0:133 offset1:134
	v_mul_f32_e32 v12, 0x3fb8aa3b, v4
	v_add_f32_e32 v4, v4, v4
	v_add_f32_e32 v5, 1.0, v5
	v_add_f32_e32 v8, 1.0, v8
	v_fmamk_f32 v14, v4, 0x3ab60b61, v122
	v_rcp_f32_e32 v5, v5
	v_rcp_f32_e32 v8, v8
	v_exp_f32_e32 v12, v12
	v_fmaak_f32 v14, v4, v14, 0x3d2aaaab
	v_fmaak_f32 v14, v4, v14, 0x3e2aaaab
	v_fma_f32 v14, v4, v14, 0.5
	v_fma_f32 v14, v4, v14, 1.0
	v_mul_f32_e32 v5, v5, v20
	v_mul_f32_e64 v14, v14, -v4
	v_fma_f32 v15, -v12, v12, 1.0
	v_cmp_lt_f32_e32 vcc, s94, v4
	v_mul_f32_e32 v8, v8, v13
	v_mul_f32_e32 v13, 0x3fb8aa3b, v5
	v_add_f32_e32 v5, v5, v5
	v_cndmask_b32_e32 v4, v15, v14, vcc
	v_add_f32_e32 v9, v9, v56
	v_fmamk_f32 v14, v5, 0x3ab60b61, v122
	v_mul_f32_e32 v9, 0xbfb8aa3b, v9
	v_exp_f32_e32 v13, v13
	v_fmaak_f32 v14, v5, v14, 0x3d2aaaab
	v_exp_f32_e32 v9, v9
	v_fmaak_f32 v14, v5, v14, 0x3e2aaaab
	v_fma_f32 v14, v5, v14, 0.5
	v_fma_f32 v14, v5, v14, 1.0
	v_mul_f32_e64 v14, v14, -v5
	v_fma_f32 v15, -v13, v13, 1.0
	v_cmp_lt_f32_e32 vcc, s94, v5
	v_add_f32_e32 v6, v6, v57
	v_max_f32_e32 v4, 0, v4
	v_add_f32_e32 v9, 1.0, v9
	v_cndmask_b32_e32 v5, v15, v14, vcc
	v_mul_f32_e32 v6, 0xbfb8aa3b, v6
	v_sqrt_f32_e32 v4, v4
	v_rcp_f32_e32 v9, v9
	v_max_f32_e32 v5, 0, v5
	v_exp_f32_e32 v6, v6
	v_sqrt_f32_e32 v5, v5
	v_mul_f32_e32 v4, v8, v4
	v_mul_f32_e32 v8, v9, v16
	v_add_f32_e32 v6, 1.0, v6
	v_mul_f32_e32 v5, v8, v5
	v_add_f32_e32 v8, v10, v56
	v_rcp_f32_e32 v6, v6
	v_add_f32_e32 v7, v7, v57
	v_mul_f32_e32 v8, 0xbfb8aa3b, v8
	v_mul_f32_e32 v7, 0xbfb8aa3b, v7
	v_exp_f32_e32 v8, v8
	v_exp_f32_e32 v7, v7
	ds_write2st64_b32 v111, v4, v5 offset0:147 offset1:148
	v_mul_f32_e32 v5, v6, v20
	v_mul_f32_e32 v6, 0x3fb8aa3b, v5
	v_add_f32_e32 v5, v5, v5
	v_add_f32_e32 v4, 1.0, v8
	v_fmamk_f32 v8, v5, 0x3ab60b61, v122
	v_add_f32_e32 v7, 1.0, v7
	v_exp_f32_e32 v6, v6
	v_fmaak_f32 v8, v5, v8, 0x3d2aaaab
	v_rcp_f32_e32 v7, v7
	v_fmaak_f32 v8, v5, v8, 0x3e2aaaab
	v_fma_f32 v8, v5, v8, 0.5
	v_fma_f32 v8, v5, v8, 1.0
	v_mul_f32_e64 v8, v8, -v5
	v_fma_f32 v9, -v6, v6, 1.0
	v_cmp_lt_f32_e32 vcc, s94, v5
	v_mul_f32_e32 v7, v7, v20
	v_rcp_f32_e32 v4, v4
	v_cndmask_b32_e32 v5, v9, v8, vcc
	v_mul_f32_e32 v9, 0x3fb8aa3b, v7
	v_add_f32_e32 v7, v7, v7
	v_add_f32_e32 v8, v11, v56
	v_fmamk_f32 v10, v7, 0x3ab60b61, v122
	v_mul_f32_e32 v8, 0xbfb8aa3b, v8
	v_exp_f32_e32 v9, v9
	v_fmaak_f32 v10, v7, v10, 0x3d2aaaab
	v_exp_f32_e32 v8, v8
	v_fmaak_f32 v10, v7, v10, 0x3e2aaaab
	v_fma_f32 v10, v7, v10, 0.5
	v_fma_f32 v10, v7, v10, 1.0
	v_mul_f32_e64 v10, v10, -v7
	v_fma_f32 v11, -v9, v9, 1.0
	v_cmp_lt_f32_e32 vcc, s94, v7
	v_max_f32_e32 v5, 0, v5
	v_add_f32_e32 v8, 1.0, v8
	v_cndmask_b32_e32 v7, v11, v10, vcc
	v_sqrt_f32_e32 v5, v5
	v_rcp_f32_e32 v8, v8
	v_max_f32_e32 v7, 0, v7
	v_sqrt_f32_e32 v7, v7
	v_mul_f32_e32 v4, v4, v17
	v_mul_f32_e32 v4, v4, v5
	v_mul_f32_e32 v5, v8, v23
	v_mul_f32_e32 v5, v5, v7
	ds_write2st64_b32 v111, v21, v18 offset0:1 offset1:2
	ds_write2st64_b32 v111, v24, v12 offset0:3 offset1:16
	ds_write2st64_b32 v111, v13, v6 offset0:17 offset1:18
	ds_write2st64_b32 v111, v9, v3 offset0:19 offset1:132
	ds_write2st64_b32 v111, v4, v5 offset0:149 offset1:150
	v_mov_b32_e32 v5, 0
	v_mov_b32_e32 v3, 1.0
	s_waitcnt lgkmcnt(0)
	s_barrier
